# FFN-up prompt epilogue: F rows stored with the nt hint (streamed out instead of dirtying L2 before the grid barrier)
# speedup vs baseline: 1.0191x; 1.0031x over previous
; #define PG8_STAGE(bufoff, gbase, voff) do { _Pragma("unroll") for (int _i = 0; _i < 2; ++_i) \
;         __builtin_amdgcn_global_load_lds((const unsigned*)((const char*)(gbase) + (voff)[_i]), (LAS unsigned*)(lds + (bufoff) + ldsw + _i * 8192), 16, 0, 0); } while (0)
; #define PG8_LDA(dst, b, h) do { _Pragma("unroll") for (int m = 0; m < 4; ++m) _Pragma("unroll") for (int k = 0; k < 2; ++k) dst[m][k] = *(const LAS bf16x8*)(lds + PG8_SA(b, h) + aoff + m * 2048 + k * 1024); } while (0)
; #define PG8_LDB(dst, b, h) do { _Pragma("unroll") for (int n = 0; n < 2; ++n) _Pragma("unroll") for (int k = 0; k < 2; ++k) dst[n][k] = *(const LAS bf16x8*)(lds + PG8_SB(b, h) + boff + n * 2048 + k * 1024); } while (0)
; #define PG8_MMA(ai, bj, At, Bt) do { __builtin_amdgcn_s_setprio(1); _Pragma("unroll") for (int m = 0; m < 4; ++m) _Pragma("unroll") for (int n = 0; n < 2; ++n) _Pragma("unroll") for (int k = 0; k < 2; ++k) \
;         acc[ai][bj][m][n] = __builtin_amdgcn_mfma_f32_16x16x32_bf16(Bt[n][k], At[m][k], acc[ai][bj][m][n], 0, 0, 0); __builtin_amdgcn_s_setprio(0); } while (0)
; #define PG8_WAIT_V(n) asm volatile("s_waitcnt vmcnt(" #n ")" ::: "memory")
; #define PG8_WAIT_L(n) asm volatile("s_waitcnt lgkmcnt(" #n ")" ::: "memory")
; template <class Epi, class S_t>
; __device__ __forceinline__ void gemm_phase(LAS unsigned char* lds, int lda, int ldb, const S_t& S, const Epi& E) {
;     ...
;         for (int t = 0; t < nt; t += 2) {
;             const bool last = (t == nt - 2);
;             const char* a1 = cA + (size_t)(t + 1) * kstep;
;             const char* a2 = last ? nA : cA + (size_t)(t + 2) * kstep; const char* b2 = last ? nB : cB + (size_t)(t + 2) * kstep;
;             const char* a3 = a2 + kstep; const char* b3 = b2 + kstep;
;             PG8_LDB(B0, 0, 0); PG8_SCHED; PG8_LDA(At, 0, 0); PG8_STAGE(PG8_SA(1, 1), a1 + hstepA, voffA);
;             PG8_WAIT_L(8); PG8_BAR; PG8_WAIT_L(0); PG8_MMA(0, 0, At, B0); PG8_BAR; PG8_SCHED;
;             PG8_LDB(B1, 0, 1); PG8_STAGE(PG8_SB(0, 0), b2, voffB);
;             PG8_BAR; PG8_WAIT_L(0); PG8_MMA(0, 1, At, B1); PG8_BAR;
;             PG8_LDA(At, 0, 1); PG8_STAGE(PG8_SA(0, 0), a2, voffA);
;             PG8_BAR; PG8_WAIT_L(0); PG8_MMA(1, 0, At, B0); PG8_BAR; PG8_SCHED;
;             PG8_STAGE(PG8_SB(0, 1), b2 + hstepB, voffB);
;             PG8_WAIT_V(6); PG8_BAR; PG8_MMA(1, 1, At, B1); PG8_BAR;
.LBB0_1200:
	ds_read_b128 v[128:131], v223
	ds_read_b128 v[132:135], v223 offset:1024
	ds_read_b128 v[136:139], v223 offset:2048
	ds_read_b128 v[140:143], v223 offset:3072
	s_add_u32 s33, s74, 0xfff80080
	s_addc_u32 s43, s75, -1
	s_cmp_eq_u32 s5, 28
	s_cselect_b32 s79, s69, s43
	s_cselect_b32 s78, s68, s33
	s_cselect_b32 s77, s71, s1
	s_cselect_b32 s76, s70, s0
	s_add_i32 m0, s7, 0xc000
	ds_read_b128 v[144:147], v246
	ds_read_b128 v[148:151], v246 offset:1024
	ds_read_b128 v[152:155], v246 offset:2048
	ds_read_b128 v[156:159], v246 offset:3072
	ds_read_b128 v[160:163], v246 offset:4096
	ds_read_b128 v[164:167], v246 offset:5120
	ds_read_b128 v[168:171], v246 offset:6144
	ds_read_b128 v[172:175], v246 offset:7168
	global_load_lds_dwordx4 v236, s[74:75]
	s_add_i32 m0, s7, 0xe000
	s_nop 0
	global_load_lds_dwordx4 v238, s[74:75]
	s_waitcnt lgkmcnt(8)
	s_barrier
	s_waitcnt lgkmcnt(0)
	s_setprio 1
	s_waitcnt lgkmcnt(0)
	v_mfma_f32_16x16x32_bf16 v[124:127], v[128:131], v[144:147], v[124:127]
	v_mfma_f32_16x16x32_bf16 v[120:123], v[136:139], v[144:147], v[120:123]
	v_mfma_f32_16x16x32_bf16 v[116:119], v[128:131], v[152:155], v[116:119]
	v_mfma_f32_16x16x32_bf16 v[108:111], v[136:139], v[152:155], v[108:111]
	v_mfma_f32_16x16x32_bf16 v[100:103], v[128:131], v[160:163], v[100:103]
	v_mfma_f32_16x16x32_bf16 v[92:95], v[136:139], v[160:163], v[92:95]
	v_mfma_f32_16x16x32_bf16 v[84:87], v[128:131], v[168:171], v[84:87]
	v_mfma_f32_16x16x32_bf16 v[76:79], v[136:139], v[168:171], v[76:79]
	v_mfma_f32_16x16x32_bf16 v[124:127], v[132:135], v[148:151], v[124:127]
	v_mfma_f32_16x16x32_bf16 v[120:123], v[140:143], v[148:151], v[120:123]
	v_mfma_f32_16x16x32_bf16 v[116:119], v[132:135], v[156:159], v[116:119]
	v_mfma_f32_16x16x32_bf16 v[108:111], v[140:143], v[156:159], v[108:111]
	v_mfma_f32_16x16x32_bf16 v[100:103], v[132:135], v[164:167], v[100:103]
	v_mfma_f32_16x16x32_bf16 v[92:95], v[140:143], v[164:167], v[92:95]
	v_mfma_f32_16x16x32_bf16 v[84:87], v[132:135], v[172:175], v[84:87]
	v_mfma_f32_16x16x32_bf16 v[76:79], v[140:143], v[172:175], v[76:79]
	s_setprio 0
	s_barrier
	s_add_i32 s33, s88, s64
	s_add_u32 s98, s76, s38
	s_addc_u32 s99, s77, s39
	s_mov_b32 m0, s33
	ds_read_b128 v[176:179], v247
	ds_read_b128 v[180:183], v247 offset:1024
	ds_read_b128 v[184:187], v247 offset:2048
	ds_read_b128 v[188:191], v247 offset:3072
	global_load_lds_dwordx4 v228, s[76:77]
	s_add_i32 m0, s33, 0x2000
	s_nop 0
	global_load_lds_dwordx4 v224, s[76:77]
	s_barrier
	s_waitcnt lgkmcnt(0)
	s_setprio 1
	s_waitcnt lgkmcnt(0)
	v_mfma_f32_16x16x32_bf16 v[112:115], v[176:179], v[144:147], v[112:115]
	v_mfma_f32_16x16x32_bf16 v[104:107], v[184:187], v[144:147], v[104:107]
	v_mfma_f32_16x16x32_bf16 v[96:99], v[176:179], v[152:155], v[96:99]
	v_mfma_f32_16x16x32_bf16 v[88:91], v[184:187], v[152:155], v[88:91]
	v_mfma_f32_16x16x32_bf16 v[80:83], v[176:179], v[160:163], v[80:83]
	v_mfma_f32_16x16x32_bf16 v[72:75], v[184:187], v[160:163], v[72:75]
	v_mfma_f32_16x16x32_bf16 v[68:71], v[176:179], v[168:171], v[68:71]
	v_mfma_f32_16x16x32_bf16 v[64:67], v[184:187], v[168:171], v[64:67]
	v_mfma_f32_16x16x32_bf16 v[112:115], v[180:183], v[148:151], v[112:115]
	v_mfma_f32_16x16x32_bf16 v[104:107], v[188:191], v[148:151], v[104:107]
	v_mfma_f32_16x16x32_bf16 v[96:99], v[180:183], v[156:159], v[96:99]
	v_mfma_f32_16x16x32_bf16 v[88:91], v[188:191], v[156:159], v[88:91]
	v_mfma_f32_16x16x32_bf16 v[80:83], v[180:183], v[164:167], v[80:83]
	v_mfma_f32_16x16x32_bf16 v[72:75], v[188:191], v[164:167], v[72:75]
	v_mfma_f32_16x16x32_bf16 v[68:71], v[180:183], v[172:175], v[68:71]
	v_mfma_f32_16x16x32_bf16 v[64:67], v[188:191], v[172:175], v[64:67]
	s_setprio 0
	s_mov_b32 m0, s7
	s_add_u32 s100, s78, s38
	s_addc_u32 s101, s79, s39
	s_barrier
	ds_read_b128 v[144:147], v246 offset:16384
	ds_read_b128 v[148:151], v246 offset:17408
	ds_read_b128 v[152:155], v246 offset:18432
	ds_read_b128 v[156:159], v246 offset:19456
	ds_read_b128 v[160:163], v246 offset:20480
	ds_read_b128 v[164:167], v246 offset:21504
	ds_read_b128 v[168:171], v246 offset:22528
	ds_read_b128 v[172:175], v246 offset:23552
	global_load_lds_dwordx4 v230, s[78:79]
	s_mov_b32 m0, s35
	s_nop 0
	global_load_lds_dwordx4 v226, s[78:79]
	s_barrier
	s_waitcnt lgkmcnt(0)
	s_setprio 1
	s_waitcnt lgkmcnt(0)
	v_mfma_f32_16x16x32_bf16 v[60:63], v[128:131], v[144:147], v[60:63]
	v_mfma_f32_16x16x32_bf16 v[56:59], v[136:139], v[144:147], v[56:59]
	v_mfma_f32_16x16x32_bf16 v[52:55], v[128:131], v[152:155], v[52:55]
	v_mfma_f32_16x16x32_bf16 v[44:47], v[136:139], v[152:155], v[44:47]
	v_mfma_f32_16x16x32_bf16 v[36:39], v[128:131], v[160:163], v[36:39]
	v_mfma_f32_16x16x32_bf16 v[28:31], v[136:139], v[160:163], v[28:31]
	v_mfma_f32_16x16x32_bf16 v[20:23], v[128:131], v[168:171], v[20:23]
	v_mfma_f32_16x16x32_bf16 v[12:15], v[136:139], v[168:171], v[12:15]
	v_mfma_f32_16x16x32_bf16 v[60:63], v[132:135], v[148:151], v[60:63]
	v_mfma_f32_16x16x32_bf16 v[56:59], v[140:143], v[148:151], v[56:59]
	v_mfma_f32_16x16x32_bf16 v[52:55], v[132:135], v[156:159], v[52:55]
	v_mfma_f32_16x16x32_bf16 v[44:47], v[140:143], v[156:159], v[44:47]
	v_mfma_f32_16x16x32_bf16 v[36:39], v[132:135], v[164:167], v[36:39]
	v_mfma_f32_16x16x32_bf16 v[28:31], v[140:143], v[164:167], v[28:31]
	v_mfma_f32_16x16x32_bf16 v[20:23], v[132:135], v[172:175], v[20:23]
	v_mfma_f32_16x16x32_bf16 v[12:15], v[140:143], v[172:175], v[12:15]
	s_setprio 0
	s_barrier
	s_add_u32 s52, s76, 0x80000
	s_addc_u32 s53, s77, 0
	s_add_i32 s33, s89, s64
	s_mov_b32 m0, s33
	s_nop 0
	global_load_lds_dwordx4 v228, s[52:53]
	s_add_i32 m0, s33, 0x2000
	s_nop 0
	global_load_lds_dwordx4 v224, s[52:53]
	s_waitcnt vmcnt(6)
	s_barrier
; #define PG8_STAGE(bufoff, gbase, voff) do { _Pragma("unroll") for (int _i = 0; _i < 2; ++_i) \
;         __builtin_amdgcn_global_load_lds((const unsigned*)((const char*)(gbase) + (voff)[_i]), (LAS unsigned*)(lds + (bufoff) + ldsw + _i * 8192), 16, 0, 0); } while (0)
; #define PG8_LDA(dst, b, h) do { _Pragma("unroll") for (int m = 0; m < 4; ++m) _Pragma("unroll") for (int k = 0; k < 2; ++k) dst[m][k] = *(const LAS bf16x8*)(lds + PG8_SA(b, h) + aoff + m * 2048 + k * 1024); } while (0)
; #define PG8_LDB(dst, b, h) do { _Pragma("unroll") for (int n = 0; n < 2; ++n) _Pragma("unroll") for (int k = 0; k < 2; ++k) dst[n][k] = *(const LAS bf16x8*)(lds + PG8_SB(b, h) + boff + n * 2048 + k * 1024); } while (0)
; #define PG8_MMA(ai, bj, At, Bt) do { __builtin_amdgcn_s_setprio(1); _Pragma("unroll") for (int m = 0; m < 4; ++m) _Pragma("unroll") for (int n = 0; n < 2; ++n) _Pragma("unroll") for (int k = 0; k < 2; ++k) \
;         acc[ai][bj][m][n] = __builtin_amdgcn_mfma_f32_16x16x32_bf16(Bt[n][k], At[m][k], acc[ai][bj][m][n], 0, 0, 0); __builtin_amdgcn_s_setprio(0); } while (0)
; #define PG8_WAIT_V(n) asm volatile("s_waitcnt vmcnt(" #n ")" ::: "memory")
; #define PG8_WAIT_L(n) asm volatile("s_waitcnt lgkmcnt(" #n ")" ::: "memory")
; template <class Epi, class S_t>
; __device__ __forceinline__ void gemm_phase(LAS unsigned char* lds, int lda, int ldb, const S_t& S, const Epi& E) {
;     ...
;             PG8_BAR; PG8_WAIT_L(0); PG8_MMA(0, 1, At, B1); PG8_BAR;
;             PG8_LDA(At, 0, 1); PG8_STAGE(PG8_SA(0, 0), a2, voffA);
;             PG8_BAR; PG8_WAIT_L(0); PG8_MMA(1, 0, At, B0); PG8_BAR; PG8_SCHED;
;             PG8_STAGE(PG8_SB(0, 1), b2 + hstepB, voffB);
;             PG8_WAIT_V(6); PG8_BAR; PG8_MMA(1, 1, At, B1); PG8_BAR;
;             PG8_LDB(B0, 1, 0); PG8_SCHED; PG8_LDA(At, 1, 0); PG8_STAGE(PG8_SA(0, 1), a2 + hstepA, voffA);
;             PG8_WAIT_L(8); PG8_BAR; PG8_WAIT_L(0); PG8_MMA(0, 0, At, B0); PG8_BAR; PG8_SCHED;
;             PG8_LDB(B1, 1, 1); PG8_STAGE(PG8_SB(1, 0), b3, voffB);
;             PG8_BAR; PG8_WAIT_L(0); PG8_MMA(0, 1, At, B1); PG8_BAR;
;             PG8_LDA(At, 1, 1); PG8_STAGE(PG8_SA(1, 0), a3, voffA);
;             PG8_BAR; PG8_WAIT_L(0); PG8_MMA(1, 0, At, B0); PG8_BAR; PG8_SCHED;
;             PG8_STAGE(PG8_SB(1, 1), b3 + hstepB, voffB);
;             PG8_WAIT_V(6); PG8_BAR; PG8_MMA(1, 1, At, B1); PG8_BAR;
	s_setprio 1
	v_mfma_f32_16x16x32_bf16 v[48:51], v[176:179], v[144:147], v[48:51]
	v_mfma_f32_16x16x32_bf16 v[40:43], v[184:187], v[144:147], v[40:43]
	v_mfma_f32_16x16x32_bf16 v[32:35], v[176:179], v[152:155], v[32:35]
	v_mfma_f32_16x16x32_bf16 v[24:27], v[184:187], v[152:155], v[24:27]
	v_mfma_f32_16x16x32_bf16 v[16:19], v[176:179], v[160:163], v[16:19]
	v_mfma_f32_16x16x32_bf16 v[8:11], v[184:187], v[160:163], v[8:11]
	v_mfma_f32_16x16x32_bf16 v[4:7], v[176:179], v[168:171], v[4:7]
	v_mfma_f32_16x16x32_bf16 v[0:3], v[184:187], v[168:171], v[0:3]
	v_mfma_f32_16x16x32_bf16 v[48:51], v[180:183], v[148:151], v[48:51]
	v_mfma_f32_16x16x32_bf16 v[40:43], v[188:191], v[148:151], v[40:43]
	v_mfma_f32_16x16x32_bf16 v[32:35], v[180:183], v[156:159], v[32:35]
	v_mfma_f32_16x16x32_bf16 v[24:27], v[188:191], v[156:159], v[24:27]
	v_mfma_f32_16x16x32_bf16 v[16:19], v[180:183], v[164:167], v[16:19]
	v_mfma_f32_16x16x32_bf16 v[8:11], v[188:191], v[164:167], v[8:11]
	v_mfma_f32_16x16x32_bf16 v[4:7], v[180:183], v[172:175], v[4:7]
	v_mfma_f32_16x16x32_bf16 v[0:3], v[188:191], v[172:175], v[0:3]
	s_setprio 0
	v_add_u32_e32 v140, s90, v215
	s_barrier
	ds_read_b128 v[128:131], v140
	ds_read_b128 v[132:135], v140 offset:1024
	ds_read_b128 v[136:139], v140 offset:2048
	ds_read_b128 v[140:143], v140 offset:3072
	s_add_u32 s52, s78, 0x80000
	s_addc_u32 s53, s79, 0
	s_mov_b32 m0, s92
	ds_read_b128 v[144:147], v246 offset:32768
	ds_read_b128 v[148:151], v246 offset:33792
	ds_read_b128 v[152:155], v246 offset:34816
	ds_read_b128 v[156:159], v246 offset:35840
	ds_read_b128 v[160:163], v246 offset:36864
	ds_read_b128 v[164:167], v246 offset:37888
	ds_read_b128 v[168:171], v246 offset:38912
	ds_read_b128 v[172:175], v246 offset:39936
	global_load_lds_dwordx4 v230, s[52:53]
	s_mov_b32 m0, s50
	s_nop 0
	global_load_lds_dwordx4 v226, s[52:53]
	s_waitcnt lgkmcnt(8)
	s_barrier
	s_waitcnt lgkmcnt(0)
	s_setprio 1
	s_waitcnt lgkmcnt(0)
	v_mfma_f32_16x16x32_bf16 v[124:127], v[128:131], v[144:147], v[124:127]
	v_mfma_f32_16x16x32_bf16 v[120:123], v[136:139], v[144:147], v[120:123]
	v_mfma_f32_16x16x32_bf16 v[116:119], v[128:131], v[152:155], v[116:119]
	v_mfma_f32_16x16x32_bf16 v[108:111], v[136:139], v[152:155], v[108:111]
	v_mfma_f32_16x16x32_bf16 v[100:103], v[128:131], v[160:163], v[100:103]
	v_mfma_f32_16x16x32_bf16 v[92:95], v[136:139], v[160:163], v[92:95]
	v_mfma_f32_16x16x32_bf16 v[84:87], v[128:131], v[168:171], v[84:87]
	v_mfma_f32_16x16x32_bf16 v[76:79], v[136:139], v[168:171], v[76:79]
	v_mfma_f32_16x16x32_bf16 v[124:127], v[132:135], v[148:151], v[124:127]
	v_mfma_f32_16x16x32_bf16 v[120:123], v[140:143], v[148:151], v[120:123]
	v_mfma_f32_16x16x32_bf16 v[116:119], v[132:135], v[156:159], v[116:119]
	v_mfma_f32_16x16x32_bf16 v[108:111], v[140:143], v[156:159], v[108:111]
	v_mfma_f32_16x16x32_bf16 v[100:103], v[132:135], v[164:167], v[100:103]
	v_mfma_f32_16x16x32_bf16 v[92:95], v[140:143], v[164:167], v[92:95]
	v_mfma_f32_16x16x32_bf16 v[84:87], v[132:135], v[172:175], v[84:87]
	v_mfma_f32_16x16x32_bf16 v[76:79], v[140:143], v[172:175], v[76:79]
	s_setprio 0
	s_barrier
	s_add_i32 s33, s90, s64
	v_add_u32_e32 v188, s91, v215
	s_mov_b32 m0, s33
	ds_read_b128 v[176:179], v188
	ds_read_b128 v[180:183], v188 offset:1024
	ds_read_b128 v[184:187], v188 offset:2048
	ds_read_b128 v[188:191], v188 offset:3072
	global_load_lds_dwordx4 v228, s[98:99]
	s_add_i32 m0, s33, 0x2000
	s_nop 0
	global_load_lds_dwordx4 v224, s[98:99]
	s_barrier
	s_waitcnt lgkmcnt(0)
	s_setprio 1
	s_waitcnt lgkmcnt(0)
	v_mfma_f32_16x16x32_bf16 v[112:115], v[176:179], v[144:147], v[112:115]
	v_mfma_f32_16x16x32_bf16 v[104:107], v[184:187], v[144:147], v[104:107]
	v_mfma_f32_16x16x32_bf16 v[96:99], v[176:179], v[152:155], v[96:99]
	v_mfma_f32_16x16x32_bf16 v[88:91], v[184:187], v[152:155], v[88:91]
	v_mfma_f32_16x16x32_bf16 v[80:83], v[176:179], v[160:163], v[80:83]
	v_mfma_f32_16x16x32_bf16 v[72:75], v[184:187], v[160:163], v[72:75]
	v_mfma_f32_16x16x32_bf16 v[68:71], v[176:179], v[168:171], v[68:71]
	v_mfma_f32_16x16x32_bf16 v[64:67], v[184:187], v[168:171], v[64:67]
	v_mfma_f32_16x16x32_bf16 v[112:115], v[180:183], v[148:151], v[112:115]
	v_mfma_f32_16x16x32_bf16 v[104:107], v[188:191], v[148:151], v[104:107]
	v_mfma_f32_16x16x32_bf16 v[96:99], v[180:183], v[156:159], v[96:99]
	v_mfma_f32_16x16x32_bf16 v[88:91], v[188:191], v[156:159], v[88:91]
	v_mfma_f32_16x16x32_bf16 v[80:83], v[180:183], v[164:167], v[80:83]
	v_mfma_f32_16x16x32_bf16 v[72:75], v[188:191], v[164:167], v[72:75]
	v_mfma_f32_16x16x32_bf16 v[68:71], v[180:183], v[172:175], v[68:71]
	v_mfma_f32_16x16x32_bf16 v[64:67], v[188:191], v[172:175], v[64:67]
	s_setprio 0
	s_mov_b32 m0, s96
	s_barrier
	ds_read_b128 v[144:147], v246 offset:49152
	ds_read_b128 v[148:151], v246 offset:50176
	ds_read_b128 v[152:155], v246 offset:51200
	ds_read_b128 v[156:159], v246 offset:52224
	ds_read_b128 v[160:163], v246 offset:53248
	ds_read_b128 v[164:167], v246 offset:54272
	ds_read_b128 v[168:171], v246 offset:55296
	ds_read_b128 v[172:175], v246 offset:56320
	global_load_lds_dwordx4 v230, s[100:101]
	s_mov_b32 m0, s97
	s_nop 0
	global_load_lds_dwordx4 v226, s[100:101]
	s_barrier
; template <class Epi, class S_t>
; __device__ __forceinline__ void gemm_phase(LAS unsigned char* lds, int lda, int ldb, const S_t& S, const Epi& E) {
;     ...
;             PG8_WAIT_V(6); PG8_BAR; PG8_MMA(1, 1, At, B1); PG8_BAR;
;             PG8_LDB(B0, 1, 0); PG8_SCHED; PG8_LDA(At, 1, 0); PG8_STAGE(PG8_SA(0, 1), a2 + hstepA, voffA);
;             PG8_WAIT_L(8); PG8_BAR; PG8_WAIT_L(0); PG8_MMA(0, 0, At, B0); PG8_BAR; PG8_SCHED;
;             PG8_LDB(B1, 1, 1); PG8_STAGE(PG8_SB(1, 0), b3, voffB);
;             PG8_BAR; PG8_WAIT_L(0); PG8_MMA(0, 1, At, B1); PG8_BAR;
;             PG8_LDA(At, 1, 1); PG8_STAGE(PG8_SA(1, 0), a3, voffA);
;             PG8_BAR; PG8_WAIT_L(0); PG8_MMA(1, 0, At, B0); PG8_BAR; PG8_SCHED;
;             PG8_STAGE(PG8_SB(1, 1), b3 + hstepB, voffB);
;             PG8_WAIT_V(6); PG8_BAR; PG8_MMA(1, 1, At, B1); PG8_BAR;
;     __device__ __forceinline__ void operator()(const f32x4 (&acc)[2][2][4][2], const Unit& u, int wr, int wc, int fr, int fq) const {
;     ...
;         const int j0 = u.pn * HALF + wc * 32 + 8 * fq;
;         u32x2 res0[8];
; #pragma unroll
;         for (int n = 0; n < 2; ++n) {
;             asm volatile("" ::: "memory");
;             const int jc = j0 + 4 * n;
;             const f32x4 wg0 = *(const f32x4*)(wconv + jc), wg1 = *(const f32x4*)(wconv + 2 * DFF + jc), wg2 = *(const f32x4*)(wconv + 4 * DFF + jc), bg = *(const f32x4*)(bconv + jc);
;             const f32x4 wv0 = *(const f32x4*)(wconv + DFF + jc), wv1 = *(const f32x4*)(wconv + 3 * DFF + jc), wv2 = *(const f32x4*)(wconv + 5 * DFF + jc), bv = *(const f32x4*)(bconv + DFF + jc);
; #pragma unroll
;             for (int ai = 0; ai < 2; ++ai)
; #pragma unroll
;                 for (int m = 0; m < 4; ++m) { const int row = row0 + ai * HALF + m * 16;
;                     const f32x4 g0 = acc[ai][0][m][n], v0 = acc[ai][1][m][n];
;                     f32x4 gp = (f32x4){0.f, 0.f, 0.f, 0.f}, vp = gp;
;                     if (m > 0) { gp = acc[ai][0][m > 0 ? m - 1 : 0][n]; vp = acc[ai][1][m > 0 ? m - 1 : 0][n]; }
;                     f32x4 f;
; #pragma unroll
;                     for (int j = 0; j < 4; ++j) {
;                         const float g1 = dpp_shr1(dpp_ror1(gp[j]), g0[j]), g2 = dpp_shr2(dpp_ror2(gp[j]), g0[j]);
;                         const float v1 = dpp_shr1(dpp_ror1(vp[j]), v0[j]), v2 = dpp_shr2(dpp_ror2(vp[j]), v0[j]);
	s_waitcnt lgkmcnt(0)
	s_setprio 1
	s_waitcnt lgkmcnt(0)
	v_mfma_f32_16x16x32_bf16 v[60:63], v[128:131], v[144:147], v[60:63]
	v_mfma_f32_16x16x32_bf16 v[56:59], v[136:139], v[144:147], v[56:59]
	v_mfma_f32_16x16x32_bf16 v[52:55], v[128:131], v[152:155], v[52:55]
	v_mfma_f32_16x16x32_bf16 v[44:47], v[136:139], v[152:155], v[44:47]
	v_mfma_f32_16x16x32_bf16 v[36:39], v[128:131], v[160:163], v[36:39]
	v_mfma_f32_16x16x32_bf16 v[28:31], v[136:139], v[160:163], v[28:31]
	v_mfma_f32_16x16x32_bf16 v[20:23], v[128:131], v[168:171], v[20:23]
	v_mfma_f32_16x16x32_bf16 v[12:15], v[136:139], v[168:171], v[12:15]
	v_mfma_f32_16x16x32_bf16 v[60:63], v[132:135], v[148:151], v[60:63]
	v_mfma_f32_16x16x32_bf16 v[56:59], v[140:143], v[148:151], v[56:59]
	v_mfma_f32_16x16x32_bf16 v[52:55], v[132:135], v[156:159], v[52:55]
	v_mfma_f32_16x16x32_bf16 v[44:47], v[140:143], v[156:159], v[44:47]
	v_mfma_f32_16x16x32_bf16 v[36:39], v[132:135], v[164:167], v[36:39]
	v_mfma_f32_16x16x32_bf16 v[28:31], v[140:143], v[164:167], v[28:31]
	v_mfma_f32_16x16x32_bf16 v[20:23], v[132:135], v[172:175], v[20:23]
	v_mfma_f32_16x16x32_bf16 v[12:15], v[140:143], v[172:175], v[12:15]
	s_setprio 0
	s_barrier
	s_add_u32 s52, s76, 0x80080
	s_addc_u32 s53, s77, 0
	s_add_i32 s33, s91, s64
	s_mov_b32 m0, s33
	s_nop 0
	global_load_lds_dwordx4 v228, s[52:53]
	s_add_i32 m0, s33, 0x2000
	s_nop 0
	global_load_lds_dwordx4 v224, s[52:53]
	s_waitcnt vmcnt(6)
	s_barrier
	s_setprio 1
	v_mfma_f32_16x16x32_bf16 v[48:51], v[176:179], v[144:147], v[48:51]
	v_mfma_f32_16x16x32_bf16 v[40:43], v[184:187], v[144:147], v[40:43]
	v_mfma_f32_16x16x32_bf16 v[32:35], v[176:179], v[152:155], v[32:35]
	v_mfma_f32_16x16x32_bf16 v[24:27], v[184:187], v[152:155], v[24:27]
	v_mfma_f32_16x16x32_bf16 v[16:19], v[176:179], v[160:163], v[16:19]
	v_mfma_f32_16x16x32_bf16 v[8:11], v[184:187], v[160:163], v[8:11]
	v_mfma_f32_16x16x32_bf16 v[4:7], v[176:179], v[168:171], v[4:7]
	v_mfma_f32_16x16x32_bf16 v[0:3], v[184:187], v[168:171], v[0:3]
	v_mfma_f32_16x16x32_bf16 v[48:51], v[180:183], v[148:151], v[48:51]
	v_mfma_f32_16x16x32_bf16 v[40:43], v[188:191], v[148:151], v[40:43]
	v_mfma_f32_16x16x32_bf16 v[32:35], v[180:183], v[156:159], v[32:35]
	v_mfma_f32_16x16x32_bf16 v[24:27], v[188:191], v[156:159], v[24:27]
	v_mfma_f32_16x16x32_bf16 v[16:19], v[180:183], v[164:167], v[16:19]
	v_mfma_f32_16x16x32_bf16 v[8:11], v[188:191], v[164:167], v[8:11]
	v_mfma_f32_16x16x32_bf16 v[4:7], v[180:183], v[172:175], v[4:7]
	v_mfma_f32_16x16x32_bf16 v[0:3], v[188:191], v[172:175], v[0:3]
	s_setprio 0
	s_add_i32 s5, s5, 2
	s_add_u32 s74, s74, 0x100
	s_addc_u32 s75, s75, 0
	s_add_u32 s0, s0, 0x100
	s_addc_u32 s1, s1, 0
	s_cmp_gt_u32 s5, 29
	s_barrier
	s_cbranch_scc0 .LBB0_1200
	s_lshl_b32 s5, s72, 8
	s_add_i32 s5, s5, s95
	v_or_b32_e32 v248, s5, v232
	s_cmp_lt_i32 s72, 32
	v_lshl_or_b32 v240, s42, 8, v219
	s_cbranch_scc0 .LBB0_1215
	v_lshl_or_b32 v130, s42, 7, v219
	v_readlane_b32 s16, v254, 33
	v_readlane_b32 s17, v254, 34
	v_readlane_b32 s18, v254, 35
	v_readlane_b32 s19, v254, 36
	v_readlane_b32 s20, v254, 37
	v_readlane_b32 s21, v254, 38
	v_readlane_b32 s22, v254, 39
	v_readlane_b32 s23, v254, 40
	v_readlane_b32 s24, v254, 41
	v_readlane_b32 s25, v254, 42
	v_readlane_b32 s26, v254, 43
	v_readlane_b32 s27, v254, 44
	v_readlane_b32 s28, v254, 45
	v_readlane_b32 s29, v254, 46
	v_readlane_b32 s30, v254, 47
	v_readlane_b32 s31, v254, 48
	v_ashrrev_i32_e32 v131, 31, v130
	s_ashr_i32 s72, s5, 6
	v_lshlrev_b64 v[128:129], 2, v[130:131]
	s_lshl_b32 s72, s72, 2
	s_add_i32 s73, s72, 8
	v_lshl_add_u64 v[132:133], s[26:27], 0, v[128:129]
	global_load_dwordx4 v[146:149], v[132:133], off
	global_load_dwordx4 v[178:181], v[132:133], off offset:16
	v_lshl_add_u64 v[134:135], s[58:59], 0, v[128:129]
	global_load_dwordx4 v[158:161], v[134:135], off
	global_load_dwordx4 v[190:193], v[134:135], off offset:16
	v_lshl_add_u64 v[136:137], s[46:47], 0, v[128:129]
	global_load_dwordx4 v[162:165], v[136:137], off
	global_load_dwordx4 v[194:197], v[136:137], off offset:16
	v_lshl_add_u64 v[132:133], s[48:49], 0, v[128:129]
	global_load_dwordx4 v[174:177], v[132:133], off
	global_load_dwordx4 v[206:209], v[132:133], off offset:16
	v_lshl_add_u64 v[134:135], s[60:61], 0, v[128:129]
	global_load_dwordx4 v[154:157], v[134:135], off
	global_load_dwordx4 v[186:189], v[134:135], off offset:16
	v_lshl_add_u64 v[136:137], s[54:55], 0, v[128:129]
	global_load_dwordx4 v[170:173], v[136:137], off
	global_load_dwordx4 v[202:205], v[136:137], off offset:16
	v_lshl_add_u64 v[132:133], s[24:25], 0, v[128:129]
	global_load_dwordx4 v[150:153], v[132:133], off
	global_load_dwordx4 v[182:185], v[132:133], off offset:16
	v_lshl_add_u64 v[134:135], s[56:57], 0, v[128:129]
	global_load_dwordx4 v[166:169], v[134:135], off
	global_load_dwordx4 v[198:201], v[134:135], off offset:16
	v_lshl_add_u64 v[242:243], v[130:131], 1, s[40:41]
	v_ashrrev_i32_e32 v241, 31, v240
	s_mov_b32 s98, 0xbdd2d3e8
	s_mov_b32 s99, 0xbdd2d3e8
	s_mov_b32 s100, 1.0
	s_mov_b32 s101, 1.0
	v_mov_b32_e32 v244, 0xc0135761
	v_mov_b32_e32 v245, 0xc0135761
	s_and_saveexec_b64 s[42:43], s[10:11]
	v_or_b32_e32 v144, s72, v232
	v_mov_b64_e32 v[128:129], s[80:81]
	v_mad_u64_u32 v[128:129], vcc, v144, s83, v[128:129]
	v_lshl_add_u64 v[128:129], v[240:241], 1, v[128:129]
	v_cvt_pk_bf16_f32 v132, v124, v125
	v_cvt_pk_bf16_f32 v133, v126, v127
	v_cvt_pk_bf16_f32 v134, v120, v121
	v_cvt_pk_bf16_f32 v135, v122, v123
	v_cvt_pk_bf16_f32 v136, v112, v113
	v_cvt_pk_bf16_f32 v137, v114, v115
	v_cvt_pk_bf16_f32 v138, v104, v105
	v_cvt_pk_bf16_f32 v139, v106, v107
	global_store_dwordx4 v[128:129], v[132:135], off
	global_store_dwordx4 v[128:129], v[136:139], off offset:256
	v_or_b32_e32 v144, s73, v232
	v_mov_b64_e32 v[130:131], s[80:81]
	v_mad_u64_u32 v[130:131], vcc, v144, s83, v[130:131]
	v_lshl_add_u64 v[130:131], v[240:241], 1, v[130:131]
	v_cvt_pk_bf16_f32 v140, v60, v61
	v_cvt_pk_bf16_f32 v141, v62, v63
	v_cvt_pk_bf16_f32 v142, v56, v57
	v_cvt_pk_bf16_f32 v143, v58, v59
	v_cvt_pk_bf16_f32 v250, v48, v49
	v_cvt_pk_bf16_f32 v251, v50, v51
	v_cvt_pk_bf16_f32 v252, v40, v41
	v_cvt_pk_bf16_f32 v253, v42, v43
	global_store_dwordx4 v[130:131], v[140:143], off
	global_store_dwordx4 v[130:131], v[250:253], off offset:256
	s_or_b64 exec, exec, s[42:43]
	s_and_saveexec_b64 s[42:43], s[12:13]
	v_add_u32_e32 v144, s72, v234
	v_mov_b64_e32 v[128:129], s[80:81]
	v_mad_u64_u32 v[128:129], vcc, v144, s83, v[128:129]
	v_lshl_add_u64 v[128:129], v[240:241], 1, v[128:129]
	v_cvt_pk_bf16_f32 v132, v84, v85
	v_cvt_pk_bf16_f32 v133, v86, v87
	v_cvt_pk_bf16_f32 v134, v76, v77
	v_cvt_pk_bf16_f32 v135, v78, v79
	v_cvt_pk_bf16_f32 v136, v68, v69
	v_cvt_pk_bf16_f32 v137, v70, v71
	v_cvt_pk_bf16_f32 v138, v64, v65
	v_cvt_pk_bf16_f32 v139, v66, v67
	global_store_dwordx4 v[128:129], v[132:135], off
	global_store_dwordx4 v[128:129], v[136:139], off offset:256
	s_or_b64 exec, exec, s[42:43]
	s_waitcnt vmcnt(6)
; __device__ __forceinline__ unsigned pk2(float lo, float hi) { unsigned r; asm("v_cvt_pk_bf16_f32 %0, %1, %2" : "=v"(r) : "v"(lo), "v"(hi)); return r; }
; __device__ __forceinline__ float gelu_tanh(float x) { const float y = 1.5957691216f * (x + 0.044715f * x * x * x); return x * __builtin_amdgcn_rcpf(1.0f + __expf(-y)); }
; __device__ __forceinline__ float dpp_shr1(float old, float src) { return __int_as_float(__builtin_amdgcn_update_dpp(__float_as_int(old), __float_as_int(src), 0x111, 0xf, 0xf, false)); }
; __device__ __forceinline__ float dpp_shr2(float old, float src) { return __int_as_float(__builtin_amdgcn_update_dpp(__float_as_int(old), __float_as_int(src), 0x112, 0xf, 0xf, false)); }
; __device__ __forceinline__ float dpp_ror1(float src) { return __int_as_float(__builtin_amdgcn_update_dpp(0, __float_as_int(src), 0x121, 0xf, 0xf, false)); }
;     __device__ __forceinline__ void operator()(const f32x4 (&acc)[2][2][4][2], const Unit& u, int wr, int wc, int fr, int fq) const {
;     ...
;                 for (int m = 0; m < 4; ++m) { const int row = row0 + ai * HALF + m * 16;
;                     const f32x4 g0 = acc[ai][0][m][n], v0 = acc[ai][1][m][n];
;                     f32x4 gp = (f32x4){0.f, 0.f, 0.f, 0.f}, vp = gp;
;                     if (m > 0) { gp = acc[ai][0][m > 0 ? m - 1 : 0][n]; vp = acc[ai][1][m > 0 ? m - 1 : 0][n]; }
;                     f32x4 f;
; #pragma unroll
;                     for (int j = 0; j < 4; ++j) {
;                         const float g1 = dpp_shr1(dpp_ror1(gp[j]), g0[j]), g2 = dpp_shr2(dpp_ror2(gp[j]), g0[j]);
;                         const float v1 = dpp_shr1(dpp_ror1(vp[j]), v0[j]), v2 = dpp_shr2(dpp_ror2(vp[j]), v0[j]);
;                         const float cg_ = bg[j] + g2 * wg0[j] + g1 * wg1[j] + g0[j] * wg2[j];
;                         const float cv_ = bv[j] + v2 * wv0[j] + v1 * wv1[j] + v0[j] * wv2[j];
;                         f[j] = gelu_tanh(cg_) * cv_; }
;                     u32x2 w; w.x = pk2(f[0], f[1]); w.y = pk2(f[2], f[3]);
;                     if (n == 0) res0[ai * 4 + m] = w;
;                     else if (m > 0 || fr >= 2) { u32x4 w4; w4.x = res0[ai * 4 + m].x; w4.y = res0[ai * 4 + m].y; w4.z = w.x; w4.w = w.y; *(u32x4*)(F + (size_t)row * DFF + j0) = w4; }
	s_nop 4
	v_pk_fma_f32 v[132:133], v[124:125], v[158:159], v[146:147]
	v_pk_fma_f32 v[136:137], v[112:113], v[174:175], v[162:163]
	v_pk_fma_f32 v[134:135], v[126:127], v[160:161], v[148:149]
	v_pk_fma_f32 v[138:139], v[114:115], v[176:177], v[164:165]
	v_fmac_f32_dpp v132, v124, v154 row_shr:1 row_mask:0xf bank_mask:0xf
	v_fmac_f32_dpp v133, v125, v155 row_shr:1 row_mask:0xf bank_mask:0xf
	v_fmac_f32_dpp v134, v126, v156 row_shr:1 row_mask:0xf bank_mask:0xf
	v_fmac_f32_dpp v135, v127, v157 row_shr:1 row_mask:0xf bank_mask:0xf
	v_fmac_f32_dpp v136, v112, v170 row_shr:1 row_mask:0xf bank_mask:0xf
	v_fmac_f32_dpp v137, v113, v171 row_shr:1 row_mask:0xf bank_mask:0xf
	v_fmac_f32_dpp v138, v114, v172 row_shr:1 row_mask:0xf bank_mask:0xf
	v_fmac_f32_dpp v139, v115, v173 row_shr:1 row_mask:0xf bank_mask:0xf
	v_fmac_f32_dpp v132, v124, v150 row_shr:2 row_mask:0xf bank_mask:0xf
	v_fmac_f32_dpp v133, v125, v151 row_shr:2 row_mask:0xf bank_mask:0xf
	v_fmac_f32_dpp v134, v126, v152 row_shr:2 row_mask:0xf bank_mask:0xf
	v_fmac_f32_dpp v135, v127, v153 row_shr:2 row_mask:0xf bank_mask:0xf
	v_fmac_f32_dpp v136, v112, v166 row_shr:2 row_mask:0xf bank_mask:0xf
	v_fmac_f32_dpp v137, v113, v167 row_shr:2 row_mask:0xf bank_mask:0xf
	v_fmac_f32_dpp v138, v114, v168 row_shr:2 row_mask:0xf bank_mask:0xf
	v_fmac_f32_dpp v139, v115, v169 row_shr:2 row_mask:0xf bank_mask:0xf
	v_pk_mul_f32 v[140:141], v[132:133], v[132:133]
	v_pk_mul_f32 v[142:143], v[134:135], v[134:135]
	v_pk_fma_f32 v[140:141], v[140:141], s[98:99], v[244:245]
	v_pk_fma_f32 v[142:143], v[142:143], s[98:99], v[244:245]
	v_pk_mul_f32 v[140:141], v[132:133], v[140:141]
	v_pk_mul_f32 v[142:143], v[134:135], v[142:143]
	v_exp_f32_e32 v140, v140
	v_exp_f32_e32 v141, v141
	v_exp_f32_e32 v142, v142
	v_exp_f32_e32 v143, v143
	v_pk_add_f32 v[140:141], v[140:141], s[100:101]
	v_pk_add_f32 v[142:143], v[142:143], s[100:101]
	v_rcp_f32_e32 v140, v140
	v_rcp_f32_e32 v141, v141
	v_rcp_f32_e32 v142, v142
	v_rcp_f32_e32 v143, v143
	v_pk_mul_f32 v[140:141], v[132:133], v[140:141]
	v_pk_mul_f32 v[142:143], v[134:135], v[142:143]
	v_pk_mul_f32 v[140:141], v[140:141], v[136:137]
	v_pk_mul_f32 v[142:143], v[142:143], v[138:139]
	v_cvt_pk_bf16_f32 v128, v140, v141
	v_cvt_pk_bf16_f32 v129, v142, v143
	v_pk_fma_f32 v[132:133], v[120:121], v[190:191], v[178:179]
	v_pk_fma_f32 v[136:137], v[104:105], v[206:207], v[194:195]
	v_pk_fma_f32 v[134:135], v[122:123], v[192:193], v[180:181]
	v_pk_fma_f32 v[138:139], v[106:107], v[208:209], v[196:197]
	v_fmac_f32_dpp v132, v120, v186 row_shr:1 row_mask:0xf bank_mask:0xf
	v_fmac_f32_dpp v133, v121, v187 row_shr:1 row_mask:0xf bank_mask:0xf
	v_fmac_f32_dpp v134, v122, v188 row_shr:1 row_mask:0xf bank_mask:0xf
	v_fmac_f32_dpp v135, v123, v189 row_shr:1 row_mask:0xf bank_mask:0xf
	v_fmac_f32_dpp v136, v104, v202 row_shr:1 row_mask:0xf bank_mask:0xf
	v_fmac_f32_dpp v137, v105, v203 row_shr:1 row_mask:0xf bank_mask:0xf
	v_fmac_f32_dpp v138, v106, v204 row_shr:1 row_mask:0xf bank_mask:0xf
	v_fmac_f32_dpp v139, v107, v205 row_shr:1 row_mask:0xf bank_mask:0xf
	v_fmac_f32_dpp v132, v120, v182 row_shr:2 row_mask:0xf bank_mask:0xf
	v_fmac_f32_dpp v133, v121, v183 row_shr:2 row_mask:0xf bank_mask:0xf
	v_fmac_f32_dpp v134, v122, v184 row_shr:2 row_mask:0xf bank_mask:0xf
	v_fmac_f32_dpp v135, v123, v185 row_shr:2 row_mask:0xf bank_mask:0xf
	v_fmac_f32_dpp v136, v104, v198 row_shr:2 row_mask:0xf bank_mask:0xf
	v_fmac_f32_dpp v137, v105, v199 row_shr:2 row_mask:0xf bank_mask:0xf
	v_fmac_f32_dpp v138, v106, v200 row_shr:2 row_mask:0xf bank_mask:0xf
	v_fmac_f32_dpp v139, v107, v201 row_shr:2 row_mask:0xf bank_mask:0xf
	v_pk_mul_f32 v[140:141], v[132:133], v[132:133]
	v_pk_mul_f32 v[142:143], v[134:135], v[134:135]
	v_pk_fma_f32 v[140:141], v[140:141], s[98:99], v[244:245]
	v_pk_fma_f32 v[142:143], v[142:143], s[98:99], v[244:245]
	v_pk_mul_f32 v[140:141], v[132:133], v[140:141]
	v_pk_mul_f32 v[142:143], v[134:135], v[142:143]
	v_exp_f32_e32 v140, v140
	v_exp_f32_e32 v141, v141
	v_exp_f32_e32 v142, v142
	v_exp_f32_e32 v143, v143
	v_pk_add_f32 v[140:141], v[140:141], s[100:101]
	v_pk_add_f32 v[142:143], v[142:143], s[100:101]
	v_rcp_f32_e32 v140, v140
	v_rcp_f32_e32 v141, v141
	v_rcp_f32_e32 v142, v142
	v_rcp_f32_e32 v143, v143
	v_pk_mul_f32 v[140:141], v[132:133], v[140:141]
	v_pk_mul_f32 v[142:143], v[134:135], v[142:143]
	v_pk_mul_f32 v[140:141], v[140:141], v[136:137]
	v_pk_mul_f32 v[142:143], v[142:143], v[138:139]
	v_cvt_pk_bf16_f32 v130, v140, v141
	v_cvt_pk_bf16_f32 v131, v142, v143
	s_and_saveexec_b64 s[42:43], s[8:9]
	v_mad_u64_u32 v[144:145], vcc, v248, s4, v[242:243]
	global_store_dwordx4 v[144:145], v[128:131], off nt
	s_or_b64 exec, exec, s[42:43]
	s_nop 4
	v_pk_fma_f32 v[132:133], v[116:117], v[158:159], v[146:147]
	v_pk_fma_f32 v[136:137], v[96:97], v[174:175], v[162:163]
	v_pk_fma_f32 v[134:135], v[118:119], v[160:161], v[148:149]
	v_pk_fma_f32 v[138:139], v[98:99], v[176:177], v[164:165]
	v_fmac_f32_dpp v132, v116, v154 row_shr:1 row_mask:0xf bank_mask:0xf
	v_fmac_f32_dpp v133, v117, v155 row_shr:1 row_mask:0xf bank_mask:0xf
	v_fmac_f32_dpp v134, v118, v156 row_shr:1 row_mask:0xf bank_mask:0xf
	v_fmac_f32_dpp v135, v119, v157 row_shr:1 row_mask:0xf bank_mask:0xf
	v_fmac_f32_dpp v136, v96, v170 row_shr:1 row_mask:0xf bank_mask:0xf
	v_fmac_f32_dpp v137, v97, v171 row_shr:1 row_mask:0xf bank_mask:0xf
	v_fmac_f32_dpp v138, v98, v172 row_shr:1 row_mask:0xf bank_mask:0xf
	v_fmac_f32_dpp v139, v99, v173 row_shr:1 row_mask:0xf bank_mask:0xf
	v_fmac_f32_dpp v132, v124, v154 row_shl:15 row_mask:0xf bank_mask:0xf
	v_fmac_f32_dpp v133, v125, v155 row_shl:15 row_mask:0xf bank_mask:0xf
; __device__ __forceinline__ unsigned pk2(float lo, float hi) { unsigned r; asm("v_cvt_pk_bf16_f32 %0, %1, %2" : "=v"(r) : "v"(lo), "v"(hi)); return r; }
; __device__ __forceinline__ float gelu_tanh(float x) { const float y = 1.5957691216f * (x + 0.044715f * x * x * x); return x * __builtin_amdgcn_rcpf(1.0f + __expf(-y)); }
; __device__ __forceinline__ float dpp_shr1(float old, float src) { return __int_as_float(__builtin_amdgcn_update_dpp(__float_as_int(old), __float_as_int(src), 0x111, 0xf, 0xf, false)); }
; __device__ __forceinline__ float dpp_shr2(float old, float src) { return __int_as_float(__builtin_amdgcn_update_dpp(__float_as_int(old), __float_as_int(src), 0x112, 0xf, 0xf, false)); }
; __device__ __forceinline__ float dpp_ror1(float src) { return __int_as_float(__builtin_amdgcn_update_dpp(0, __float_as_int(src), 0x121, 0xf, 0xf, false)); }
;     __device__ __forceinline__ void operator()(const f32x4 (&acc)[2][2][4][2], const Unit& u, int wr, int wc, int fr, int fq) const {
;     ...
;                 for (int m = 0; m < 4; ++m) { const int row = row0 + ai * HALF + m * 16;
;                     const f32x4 g0 = acc[ai][0][m][n], v0 = acc[ai][1][m][n];
;                     f32x4 gp = (f32x4){0.f, 0.f, 0.f, 0.f}, vp = gp;
;                     if (m > 0) { gp = acc[ai][0][m > 0 ? m - 1 : 0][n]; vp = acc[ai][1][m > 0 ? m - 1 : 0][n]; }
;                     f32x4 f;
; #pragma unroll
;                     for (int j = 0; j < 4; ++j) {
;                         const float g1 = dpp_shr1(dpp_ror1(gp[j]), g0[j]), g2 = dpp_shr2(dpp_ror2(gp[j]), g0[j]);
;                         const float v1 = dpp_shr1(dpp_ror1(vp[j]), v0[j]), v2 = dpp_shr2(dpp_ror2(vp[j]), v0[j]);
;                         const float cg_ = bg[j] + g2 * wg0[j] + g1 * wg1[j] + g0[j] * wg2[j];
;                         const float cv_ = bv[j] + v2 * wv0[j] + v1 * wv1[j] + v0[j] * wv2[j];
;                         f[j] = gelu_tanh(cg_) * cv_; }
;                     u32x2 w; w.x = pk2(f[0], f[1]); w.y = pk2(f[2], f[3]);
;                     if (n == 0) res0[ai * 4 + m] = w;
;                     else if (m > 0 || fr >= 2) { u32x4 w4; w4.x = res0[ai * 4 + m].x; w4.y = res0[ai * 4 + m].y; w4.z = w.x; w4.w = w.y; *(u32x4*)(F + (size_t)row * DFF + j0) = w4; }
	v_fmac_f32_dpp v134, v126, v156 row_shl:15 row_mask:0xf bank_mask:0xf
	v_fmac_f32_dpp v135, v127, v157 row_shl:15 row_mask:0xf bank_mask:0xf
	v_fmac_f32_dpp v136, v112, v170 row_shl:15 row_mask:0xf bank_mask:0xf
	v_fmac_f32_dpp v137, v113, v171 row_shl:15 row_mask:0xf bank_mask:0xf
	v_fmac_f32_dpp v138, v114, v172 row_shl:15 row_mask:0xf bank_mask:0xf
	v_fmac_f32_dpp v139, v115, v173 row_shl:15 row_mask:0xf bank_mask:0xf
	v_fmac_f32_dpp v132, v116, v150 row_shr:2 row_mask:0xf bank_mask:0xf
	v_fmac_f32_dpp v133, v117, v151 row_shr:2 row_mask:0xf bank_mask:0xf
	v_fmac_f32_dpp v134, v118, v152 row_shr:2 row_mask:0xf bank_mask:0xf
	v_fmac_f32_dpp v135, v119, v153 row_shr:2 row_mask:0xf bank_mask:0xf
	v_fmac_f32_dpp v136, v96, v166 row_shr:2 row_mask:0xf bank_mask:0xf
	v_fmac_f32_dpp v137, v97, v167 row_shr:2 row_mask:0xf bank_mask:0xf
	v_fmac_f32_dpp v138, v98, v168 row_shr:2 row_mask:0xf bank_mask:0xf
	v_fmac_f32_dpp v139, v99, v169 row_shr:2 row_mask:0xf bank_mask:0xf
	v_fmac_f32_dpp v132, v124, v150 row_shl:14 row_mask:0xf bank_mask:0xf
	v_fmac_f32_dpp v133, v125, v151 row_shl:14 row_mask:0xf bank_mask:0xf
	v_fmac_f32_dpp v134, v126, v152 row_shl:14 row_mask:0xf bank_mask:0xf
	v_fmac_f32_dpp v135, v127, v153 row_shl:14 row_mask:0xf bank_mask:0xf
	v_fmac_f32_dpp v136, v112, v166 row_shl:14 row_mask:0xf bank_mask:0xf
	v_fmac_f32_dpp v137, v113, v167 row_shl:14 row_mask:0xf bank_mask:0xf
	v_fmac_f32_dpp v138, v114, v168 row_shl:14 row_mask:0xf bank_mask:0xf
	v_fmac_f32_dpp v139, v115, v169 row_shl:14 row_mask:0xf bank_mask:0xf
	v_pk_mul_f32 v[140:141], v[132:133], v[132:133]
	v_pk_mul_f32 v[142:143], v[134:135], v[134:135]
	v_pk_fma_f32 v[140:141], v[140:141], s[98:99], v[244:245]
	v_pk_fma_f32 v[142:143], v[142:143], s[98:99], v[244:245]
	v_pk_mul_f32 v[140:141], v[132:133], v[140:141]
	v_pk_mul_f32 v[142:143], v[134:135], v[142:143]
	v_exp_f32_e32 v140, v140
	v_exp_f32_e32 v141, v141
	v_exp_f32_e32 v142, v142
	v_exp_f32_e32 v143, v143
	v_pk_add_f32 v[140:141], v[140:141], s[100:101]
	v_pk_add_f32 v[142:143], v[142:143], s[100:101]
	v_rcp_f32_e32 v140, v140
	v_rcp_f32_e32 v141, v141
	v_rcp_f32_e32 v142, v142
	v_rcp_f32_e32 v143, v143
	v_pk_mul_f32 v[140:141], v[132:133], v[140:141]
	v_pk_mul_f32 v[142:143], v[134:135], v[142:143]
	v_pk_mul_f32 v[140:141], v[140:141], v[136:137]
	v_pk_mul_f32 v[142:143], v[142:143], v[138:139]
	v_cvt_pk_bf16_f32 v250, v140, v141
	v_cvt_pk_bf16_f32 v251, v142, v143
	v_pk_fma_f32 v[132:133], v[108:109], v[190:191], v[178:179]
	v_pk_fma_f32 v[136:137], v[88:89], v[206:207], v[194:195]
	v_pk_fma_f32 v[134:135], v[110:111], v[192:193], v[180:181]
	v_pk_fma_f32 v[138:139], v[90:91], v[208:209], v[196:197]
	v_fmac_f32_dpp v132, v108, v186 row_shr:1 row_mask:0xf bank_mask:0xf
	v_fmac_f32_dpp v133, v109, v187 row_shr:1 row_mask:0xf bank_mask:0xf
	v_fmac_f32_dpp v134, v110, v188 row_shr:1 row_mask:0xf bank_mask:0xf
	v_fmac_f32_dpp v135, v111, v189 row_shr:1 row_mask:0xf bank_mask:0xf
	v_fmac_f32_dpp v136, v88, v202 row_shr:1 row_mask:0xf bank_mask:0xf
	v_fmac_f32_dpp v137, v89, v203 row_shr:1 row_mask:0xf bank_mask:0xf
	v_fmac_f32_dpp v138, v90, v204 row_shr:1 row_mask:0xf bank_mask:0xf
	v_fmac_f32_dpp v139, v91, v205 row_shr:1 row_mask:0xf bank_mask:0xf
	v_fmac_f32_dpp v132, v120, v186 row_shl:15 row_mask:0xf bank_mask:0xf
	v_fmac_f32_dpp v133, v121, v187 row_shl:15 row_mask:0xf bank_mask:0xf
	v_fmac_f32_dpp v134, v122, v188 row_shl:15 row_mask:0xf bank_mask:0xf
	v_fmac_f32_dpp v135, v123, v189 row_shl:15 row_mask:0xf bank_mask:0xf
	v_fmac_f32_dpp v136, v104, v202 row_shl:15 row_mask:0xf bank_mask:0xf
	v_fmac_f32_dpp v137, v105, v203 row_shl:15 row_mask:0xf bank_mask:0xf
	v_fmac_f32_dpp v138, v106, v204 row_shl:15 row_mask:0xf bank_mask:0xf
	v_fmac_f32_dpp v139, v107, v205 row_shl:15 row_mask:0xf bank_mask:0xf
	v_fmac_f32_dpp v132, v108, v182 row_shr:2 row_mask:0xf bank_mask:0xf
	v_fmac_f32_dpp v133, v109, v183 row_shr:2 row_mask:0xf bank_mask:0xf
	v_fmac_f32_dpp v134, v110, v184 row_shr:2 row_mask:0xf bank_mask:0xf
	v_fmac_f32_dpp v135, v111, v185 row_shr:2 row_mask:0xf bank_mask:0xf
	v_fmac_f32_dpp v136, v88, v198 row_shr:2 row_mask:0xf bank_mask:0xf
	v_fmac_f32_dpp v137, v89, v199 row_shr:2 row_mask:0xf bank_mask:0xf
	v_fmac_f32_dpp v138, v90, v200 row_shr:2 row_mask:0xf bank_mask:0xf
	v_fmac_f32_dpp v139, v91, v201 row_shr:2 row_mask:0xf bank_mask:0xf
	v_fmac_f32_dpp v132, v120, v182 row_shl:14 row_mask:0xf bank_mask:0xf
	v_fmac_f32_dpp v133, v121, v183 row_shl:14 row_mask:0xf bank_mask:0xf
	v_fmac_f32_dpp v134, v122, v184 row_shl:14 row_mask:0xf bank_mask:0xf
	v_fmac_f32_dpp v135, v123, v185 row_shl:14 row_mask:0xf bank_mask:0xf
	v_fmac_f32_dpp v136, v104, v198 row_shl:14 row_mask:0xf bank_mask:0xf
	v_fmac_f32_dpp v137, v105, v199 row_shl:14 row_mask:0xf bank_mask:0xf
	v_fmac_f32_dpp v138, v106, v200 row_shl:14 row_mask:0xf bank_mask:0xf
	v_fmac_f32_dpp v139, v107, v201 row_shl:14 row_mask:0xf bank_mask:0xf
	v_pk_mul_f32 v[140:141], v[132:133], v[132:133]
	v_pk_mul_f32 v[142:143], v[134:135], v[134:135]
	v_pk_fma_f32 v[140:141], v[140:141], s[98:99], v[244:245]
	v_pk_fma_f32 v[142:143], v[142:143], s[98:99], v[244:245]
	v_pk_mul_f32 v[140:141], v[132:133], v[140:141]
	v_pk_mul_f32 v[142:143], v[134:135], v[142:143]
	v_exp_f32_e32 v140, v140
	v_exp_f32_e32 v141, v141
	v_exp_f32_e32 v142, v142
	v_exp_f32_e32 v143, v143
	v_pk_add_f32 v[140:141], v[140:141], s[100:101]
	v_pk_add_f32 v[142:143], v[142:143], s[100:101]
	v_rcp_f32_e32 v140, v140
	v_rcp_f32_e32 v141, v141
	v_rcp_f32_e32 v142, v142
	v_rcp_f32_e32 v143, v143
	v_pk_mul_f32 v[140:141], v[132:133], v[140:141]
	v_pk_mul_f32 v[142:143], v[134:135], v[142:143]
; __device__ __forceinline__ unsigned pk2(float lo, float hi) { unsigned r; asm("v_cvt_pk_bf16_f32 %0, %1, %2" : "=v"(r) : "v"(lo), "v"(hi)); return r; }
; __device__ __forceinline__ float gelu_tanh(float x) { const float y = 1.5957691216f * (x + 0.044715f * x * x * x); return x * __builtin_amdgcn_rcpf(1.0f + __expf(-y)); }
; __device__ __forceinline__ float dpp_shr1(float old, float src) { return __int_as_float(__builtin_amdgcn_update_dpp(__float_as_int(old), __float_as_int(src), 0x111, 0xf, 0xf, false)); }
; __device__ __forceinline__ float dpp_shr2(float old, float src) { return __int_as_float(__builtin_amdgcn_update_dpp(__float_as_int(old), __float_as_int(src), 0x112, 0xf, 0xf, false)); }
; __device__ __forceinline__ float dpp_ror1(float src) { return __int_as_float(__builtin_amdgcn_update_dpp(0, __float_as_int(src), 0x121, 0xf, 0xf, false)); }
;     __device__ __forceinline__ void operator()(const f32x4 (&acc)[2][2][4][2], const Unit& u, int wr, int wc, int fr, int fq) const {
;     ...
;                 for (int m = 0; m < 4; ++m) { const int row = row0 + ai * HALF + m * 16;
;                     const f32x4 g0 = acc[ai][0][m][n], v0 = acc[ai][1][m][n];
;                     f32x4 gp = (f32x4){0.f, 0.f, 0.f, 0.f}, vp = gp;
;                     if (m > 0) { gp = acc[ai][0][m > 0 ? m - 1 : 0][n]; vp = acc[ai][1][m > 0 ? m - 1 : 0][n]; }
;                     f32x4 f;
; #pragma unroll
;                     for (int j = 0; j < 4; ++j) {
;                         const float g1 = dpp_shr1(dpp_ror1(gp[j]), g0[j]), g2 = dpp_shr2(dpp_ror2(gp[j]), g0[j]);
;                         const float v1 = dpp_shr1(dpp_ror1(vp[j]), v0[j]), v2 = dpp_shr2(dpp_ror2(vp[j]), v0[j]);
;                         const float cg_ = bg[j] + g2 * wg0[j] + g1 * wg1[j] + g0[j] * wg2[j];
;                         const float cv_ = bv[j] + v2 * wv0[j] + v1 * wv1[j] + v0[j] * wv2[j];
;                         f[j] = gelu_tanh(cg_) * cv_; }
;                     u32x2 w; w.x = pk2(f[0], f[1]); w.y = pk2(f[2], f[3]);
;                     if (n == 0) res0[ai * 4 + m] = w;
;                     else if (m > 0 || fr >= 2) { u32x4 w4; w4.x = res0[ai * 4 + m].x; w4.y = res0[ai * 4 + m].y; w4.z = w.x; w4.w = w.y; *(u32x4*)(F + (size_t)row * DFF + j0) = w4; }
	v_pk_mul_f32 v[140:141], v[140:141], v[136:137]
	v_pk_mul_f32 v[142:143], v[142:143], v[138:139]
	v_cvt_pk_bf16_f32 v252, v140, v141
	v_cvt_pk_bf16_f32 v253, v142, v143
	v_add_u32_e32 v144, 0x10, v248
	v_mad_u64_u32 v[144:145], vcc, v144, s4, v[242:243]
	global_store_dwordx4 v[144:145], v[250:253], off nt
	v_pk_fma_f32 v[132:133], v[100:101], v[158:159], v[146:147]
	v_pk_fma_f32 v[136:137], v[80:81], v[174:175], v[162:163]
	v_pk_fma_f32 v[134:135], v[102:103], v[160:161], v[148:149]
	v_pk_fma_f32 v[138:139], v[82:83], v[176:177], v[164:165]
	v_fmac_f32_dpp v132, v100, v154 row_shr:1 row_mask:0xf bank_mask:0xf
	v_fmac_f32_dpp v133, v101, v155 row_shr:1 row_mask:0xf bank_mask:0xf
	v_fmac_f32_dpp v134, v102, v156 row_shr:1 row_mask:0xf bank_mask:0xf
	v_fmac_f32_dpp v135, v103, v157 row_shr:1 row_mask:0xf bank_mask:0xf
	v_fmac_f32_dpp v136, v80, v170 row_shr:1 row_mask:0xf bank_mask:0xf
	v_fmac_f32_dpp v137, v81, v171 row_shr:1 row_mask:0xf bank_mask:0xf
	v_fmac_f32_dpp v138, v82, v172 row_shr:1 row_mask:0xf bank_mask:0xf
	v_fmac_f32_dpp v139, v83, v173 row_shr:1 row_mask:0xf bank_mask:0xf
	v_fmac_f32_dpp v132, v116, v154 row_shl:15 row_mask:0xf bank_mask:0xf
	v_fmac_f32_dpp v133, v117, v155 row_shl:15 row_mask:0xf bank_mask:0xf
	v_fmac_f32_dpp v134, v118, v156 row_shl:15 row_mask:0xf bank_mask:0xf
	v_fmac_f32_dpp v135, v119, v157 row_shl:15 row_mask:0xf bank_mask:0xf
	v_fmac_f32_dpp v136, v96, v170 row_shl:15 row_mask:0xf bank_mask:0xf
	v_fmac_f32_dpp v137, v97, v171 row_shl:15 row_mask:0xf bank_mask:0xf
	v_fmac_f32_dpp v138, v98, v172 row_shl:15 row_mask:0xf bank_mask:0xf
	v_fmac_f32_dpp v139, v99, v173 row_shl:15 row_mask:0xf bank_mask:0xf
	v_fmac_f32_dpp v132, v100, v150 row_shr:2 row_mask:0xf bank_mask:0xf
	v_fmac_f32_dpp v133, v101, v151 row_shr:2 row_mask:0xf bank_mask:0xf
	v_fmac_f32_dpp v134, v102, v152 row_shr:2 row_mask:0xf bank_mask:0xf
	v_fmac_f32_dpp v135, v103, v153 row_shr:2 row_mask:0xf bank_mask:0xf
	v_fmac_f32_dpp v136, v80, v166 row_shr:2 row_mask:0xf bank_mask:0xf
	v_fmac_f32_dpp v137, v81, v167 row_shr:2 row_mask:0xf bank_mask:0xf
	v_fmac_f32_dpp v138, v82, v168 row_shr:2 row_mask:0xf bank_mask:0xf
	v_fmac_f32_dpp v139, v83, v169 row_shr:2 row_mask:0xf bank_mask:0xf
	v_fmac_f32_dpp v132, v116, v150 row_shl:14 row_mask:0xf bank_mask:0xf
	v_fmac_f32_dpp v133, v117, v151 row_shl:14 row_mask:0xf bank_mask:0xf
	v_fmac_f32_dpp v134, v118, v152 row_shl:14 row_mask:0xf bank_mask:0xf
	v_fmac_f32_dpp v135, v119, v153 row_shl:14 row_mask:0xf bank_mask:0xf
	v_fmac_f32_dpp v136, v96, v166 row_shl:14 row_mask:0xf bank_mask:0xf
	v_fmac_f32_dpp v137, v97, v167 row_shl:14 row_mask:0xf bank_mask:0xf
	v_fmac_f32_dpp v138, v98, v168 row_shl:14 row_mask:0xf bank_mask:0xf
	v_fmac_f32_dpp v139, v99, v169 row_shl:14 row_mask:0xf bank_mask:0xf
	v_pk_mul_f32 v[140:141], v[132:133], v[132:133]
	v_pk_mul_f32 v[142:143], v[134:135], v[134:135]
	v_pk_fma_f32 v[140:141], v[140:141], s[98:99], v[244:245]
	v_pk_fma_f32 v[142:143], v[142:143], s[98:99], v[244:245]
	v_pk_mul_f32 v[140:141], v[132:133], v[140:141]
	v_pk_mul_f32 v[142:143], v[134:135], v[142:143]
	v_exp_f32_e32 v140, v140
	v_exp_f32_e32 v141, v141
	v_exp_f32_e32 v142, v142
	v_exp_f32_e32 v143, v143
	v_pk_add_f32 v[140:141], v[140:141], s[100:101]
	v_pk_add_f32 v[142:143], v[142:143], s[100:101]
	v_rcp_f32_e32 v140, v140
	v_rcp_f32_e32 v141, v141
	v_rcp_f32_e32 v142, v142
	v_rcp_f32_e32 v143, v143
	v_pk_mul_f32 v[140:141], v[132:133], v[140:141]
	v_pk_mul_f32 v[142:143], v[134:135], v[142:143]
	v_pk_mul_f32 v[140:141], v[140:141], v[136:137]
	v_pk_mul_f32 v[142:143], v[142:143], v[138:139]
	v_cvt_pk_bf16_f32 v128, v140, v141
	v_cvt_pk_bf16_f32 v129, v142, v143
	v_pk_fma_f32 v[132:133], v[92:93], v[190:191], v[178:179]
	v_pk_fma_f32 v[136:137], v[72:73], v[206:207], v[194:195]
	v_pk_fma_f32 v[134:135], v[94:95], v[192:193], v[180:181]
	v_pk_fma_f32 v[138:139], v[74:75], v[208:209], v[196:197]
	v_fmac_f32_dpp v132, v92, v186 row_shr:1 row_mask:0xf bank_mask:0xf
	v_fmac_f32_dpp v133, v93, v187 row_shr:1 row_mask:0xf bank_mask:0xf
	v_fmac_f32_dpp v134, v94, v188 row_shr:1 row_mask:0xf bank_mask:0xf
	v_fmac_f32_dpp v135, v95, v189 row_shr:1 row_mask:0xf bank_mask:0xf
	v_fmac_f32_dpp v136, v72, v202 row_shr:1 row_mask:0xf bank_mask:0xf
	v_fmac_f32_dpp v137, v73, v203 row_shr:1 row_mask:0xf bank_mask:0xf
	v_fmac_f32_dpp v138, v74, v204 row_shr:1 row_mask:0xf bank_mask:0xf
	v_fmac_f32_dpp v139, v75, v205 row_shr:1 row_mask:0xf bank_mask:0xf
	v_fmac_f32_dpp v132, v108, v186 row_shl:15 row_mask:0xf bank_mask:0xf
	v_fmac_f32_dpp v133, v109, v187 row_shl:15 row_mask:0xf bank_mask:0xf
	v_fmac_f32_dpp v134, v110, v188 row_shl:15 row_mask:0xf bank_mask:0xf
	v_fmac_f32_dpp v135, v111, v189 row_shl:15 row_mask:0xf bank_mask:0xf
	v_fmac_f32_dpp v136, v88, v202 row_shl:15 row_mask:0xf bank_mask:0xf
	v_fmac_f32_dpp v137, v89, v203 row_shl:15 row_mask:0xf bank_mask:0xf
	v_fmac_f32_dpp v138, v90, v204 row_shl:15 row_mask:0xf bank_mask:0xf
	v_fmac_f32_dpp v139, v91, v205 row_shl:15 row_mask:0xf bank_mask:0xf
	v_fmac_f32_dpp v132, v92, v182 row_shr:2 row_mask:0xf bank_mask:0xf
	v_fmac_f32_dpp v133, v93, v183 row_shr:2 row_mask:0xf bank_mask:0xf
	v_fmac_f32_dpp v134, v94, v184 row_shr:2 row_mask:0xf bank_mask:0xf
	v_fmac_f32_dpp v135, v95, v185 row_shr:2 row_mask:0xf bank_mask:0xf
	v_fmac_f32_dpp v136, v72, v198 row_shr:2 row_mask:0xf bank_mask:0xf
	v_fmac_f32_dpp v137, v73, v199 row_shr:2 row_mask:0xf bank_mask:0xf
	v_fmac_f32_dpp v138, v74, v200 row_shr:2 row_mask:0xf bank_mask:0xf
	v_fmac_f32_dpp v139, v75, v201 row_shr:2 row_mask:0xf bank_mask:0xf
	v_fmac_f32_dpp v132, v108, v182 row_shl:14 row_mask:0xf bank_mask:0xf
; __device__ __forceinline__ unsigned pk2(float lo, float hi) { unsigned r; asm("v_cvt_pk_bf16_f32 %0, %1, %2" : "=v"(r) : "v"(lo), "v"(hi)); return r; }
; __device__ __forceinline__ float gelu_tanh(float x) { const float y = 1.5957691216f * (x + 0.044715f * x * x * x); return x * __builtin_amdgcn_rcpf(1.0f + __expf(-y)); }
; __device__ __forceinline__ float dpp_shr1(float old, float src) { return __int_as_float(__builtin_amdgcn_update_dpp(__float_as_int(old), __float_as_int(src), 0x111, 0xf, 0xf, false)); }
; __device__ __forceinline__ float dpp_shr2(float old, float src) { return __int_as_float(__builtin_amdgcn_update_dpp(__float_as_int(old), __float_as_int(src), 0x112, 0xf, 0xf, false)); }
; __device__ __forceinline__ float dpp_ror1(float src) { return __int_as_float(__builtin_amdgcn_update_dpp(0, __float_as_int(src), 0x121, 0xf, 0xf, false)); }
;     __device__ __forceinline__ void operator()(const f32x4 (&acc)[2][2][4][2], const Unit& u, int wr, int wc, int fr, int fq) const {
;     ...
;                 for (int m = 0; m < 4; ++m) { const int row = row0 + ai * HALF + m * 16;
;                     const f32x4 g0 = acc[ai][0][m][n], v0 = acc[ai][1][m][n];
;                     f32x4 gp = (f32x4){0.f, 0.f, 0.f, 0.f}, vp = gp;
;                     if (m > 0) { gp = acc[ai][0][m > 0 ? m - 1 : 0][n]; vp = acc[ai][1][m > 0 ? m - 1 : 0][n]; }
;                     f32x4 f;
; #pragma unroll
;                     for (int j = 0; j < 4; ++j) {
;                         const float g1 = dpp_shr1(dpp_ror1(gp[j]), g0[j]), g2 = dpp_shr2(dpp_ror2(gp[j]), g0[j]);
;                         const float v1 = dpp_shr1(dpp_ror1(vp[j]), v0[j]), v2 = dpp_shr2(dpp_ror2(vp[j]), v0[j]);
;                         const float cg_ = bg[j] + g2 * wg0[j] + g1 * wg1[j] + g0[j] * wg2[j];
;                         const float cv_ = bv[j] + v2 * wv0[j] + v1 * wv1[j] + v0[j] * wv2[j];
;                         f[j] = gelu_tanh(cg_) * cv_; }
;                     u32x2 w; w.x = pk2(f[0], f[1]); w.y = pk2(f[2], f[3]);
;                     if (n == 0) res0[ai * 4 + m] = w;
;                     else if (m > 0 || fr >= 2) { u32x4 w4; w4.x = res0[ai * 4 + m].x; w4.y = res0[ai * 4 + m].y; w4.z = w.x; w4.w = w.y; *(u32x4*)(F + (size_t)row * DFF + j0) = w4; }
	v_fmac_f32_dpp v133, v109, v183 row_shl:14 row_mask:0xf bank_mask:0xf
	v_fmac_f32_dpp v134, v110, v184 row_shl:14 row_mask:0xf bank_mask:0xf
	v_fmac_f32_dpp v135, v111, v185 row_shl:14 row_mask:0xf bank_mask:0xf
	v_fmac_f32_dpp v136, v88, v198 row_shl:14 row_mask:0xf bank_mask:0xf
	v_fmac_f32_dpp v137, v89, v199 row_shl:14 row_mask:0xf bank_mask:0xf
	v_fmac_f32_dpp v138, v90, v200 row_shl:14 row_mask:0xf bank_mask:0xf
	v_fmac_f32_dpp v139, v91, v201 row_shl:14 row_mask:0xf bank_mask:0xf
	v_pk_mul_f32 v[140:141], v[132:133], v[132:133]
	v_pk_mul_f32 v[142:143], v[134:135], v[134:135]
	v_pk_fma_f32 v[140:141], v[140:141], s[98:99], v[244:245]
	v_pk_fma_f32 v[142:143], v[142:143], s[98:99], v[244:245]
	v_pk_mul_f32 v[140:141], v[132:133], v[140:141]
	v_pk_mul_f32 v[142:143], v[134:135], v[142:143]
	v_exp_f32_e32 v140, v140
	v_exp_f32_e32 v141, v141
	v_exp_f32_e32 v142, v142
	v_exp_f32_e32 v143, v143
	v_pk_add_f32 v[140:141], v[140:141], s[100:101]
	v_pk_add_f32 v[142:143], v[142:143], s[100:101]
	v_rcp_f32_e32 v140, v140
	v_rcp_f32_e32 v141, v141
	v_rcp_f32_e32 v142, v142
	v_rcp_f32_e32 v143, v143
	v_pk_mul_f32 v[140:141], v[132:133], v[140:141]
	v_pk_mul_f32 v[142:143], v[134:135], v[142:143]
	v_pk_mul_f32 v[140:141], v[140:141], v[136:137]
	v_pk_mul_f32 v[142:143], v[142:143], v[138:139]
	v_cvt_pk_bf16_f32 v130, v140, v141
	v_cvt_pk_bf16_f32 v131, v142, v143
	v_add_u32_e32 v144, 0x20, v248
	v_mad_u64_u32 v[144:145], vcc, v144, s4, v[242:243]
	global_store_dwordx4 v[144:145], v[128:131], off nt
	v_pk_fma_f32 v[132:133], v[84:85], v[158:159], v[146:147]
	v_pk_fma_f32 v[136:137], v[68:69], v[174:175], v[162:163]
	v_pk_fma_f32 v[134:135], v[86:87], v[160:161], v[148:149]
	v_pk_fma_f32 v[138:139], v[70:71], v[176:177], v[164:165]
	v_fmac_f32_dpp v132, v84, v154 row_shr:1 row_mask:0xf bank_mask:0xf
	v_fmac_f32_dpp v133, v85, v155 row_shr:1 row_mask:0xf bank_mask:0xf
	v_fmac_f32_dpp v134, v86, v156 row_shr:1 row_mask:0xf bank_mask:0xf
	v_fmac_f32_dpp v135, v87, v157 row_shr:1 row_mask:0xf bank_mask:0xf
	v_fmac_f32_dpp v136, v68, v170 row_shr:1 row_mask:0xf bank_mask:0xf
	v_fmac_f32_dpp v137, v69, v171 row_shr:1 row_mask:0xf bank_mask:0xf
	v_fmac_f32_dpp v138, v70, v172 row_shr:1 row_mask:0xf bank_mask:0xf
	v_fmac_f32_dpp v139, v71, v173 row_shr:1 row_mask:0xf bank_mask:0xf
	v_fmac_f32_dpp v132, v100, v154 row_shl:15 row_mask:0xf bank_mask:0xf
	v_fmac_f32_dpp v133, v101, v155 row_shl:15 row_mask:0xf bank_mask:0xf
	v_fmac_f32_dpp v134, v102, v156 row_shl:15 row_mask:0xf bank_mask:0xf
	v_fmac_f32_dpp v135, v103, v157 row_shl:15 row_mask:0xf bank_mask:0xf
	v_fmac_f32_dpp v136, v80, v170 row_shl:15 row_mask:0xf bank_mask:0xf
	v_fmac_f32_dpp v137, v81, v171 row_shl:15 row_mask:0xf bank_mask:0xf
	v_fmac_f32_dpp v138, v82, v172 row_shl:15 row_mask:0xf bank_mask:0xf
	v_fmac_f32_dpp v139, v83, v173 row_shl:15 row_mask:0xf bank_mask:0xf
	v_fmac_f32_dpp v132, v84, v150 row_shr:2 row_mask:0xf bank_mask:0xf
	v_fmac_f32_dpp v133, v85, v151 row_shr:2 row_mask:0xf bank_mask:0xf
	v_fmac_f32_dpp v134, v86, v152 row_shr:2 row_mask:0xf bank_mask:0xf
	v_fmac_f32_dpp v135, v87, v153 row_shr:2 row_mask:0xf bank_mask:0xf
	v_fmac_f32_dpp v136, v68, v166 row_shr:2 row_mask:0xf bank_mask:0xf
	v_fmac_f32_dpp v137, v69, v167 row_shr:2 row_mask:0xf bank_mask:0xf
	v_fmac_f32_dpp v138, v70, v168 row_shr:2 row_mask:0xf bank_mask:0xf
	v_fmac_f32_dpp v139, v71, v169 row_shr:2 row_mask:0xf bank_mask:0xf
	v_fmac_f32_dpp v132, v100, v150 row_shl:14 row_mask:0xf bank_mask:0xf
	v_fmac_f32_dpp v133, v101, v151 row_shl:14 row_mask:0xf bank_mask:0xf
	v_fmac_f32_dpp v134, v102, v152 row_shl:14 row_mask:0xf bank_mask:0xf
	v_fmac_f32_dpp v135, v103, v153 row_shl:14 row_mask:0xf bank_mask:0xf
	v_fmac_f32_dpp v136, v80, v166 row_shl:14 row_mask:0xf bank_mask:0xf
	v_fmac_f32_dpp v137, v81, v167 row_shl:14 row_mask:0xf bank_mask:0xf
	v_fmac_f32_dpp v138, v82, v168 row_shl:14 row_mask:0xf bank_mask:0xf
	v_fmac_f32_dpp v139, v83, v169 row_shl:14 row_mask:0xf bank_mask:0xf
	v_pk_mul_f32 v[140:141], v[132:133], v[132:133]
	v_pk_mul_f32 v[142:143], v[134:135], v[134:135]
	v_pk_fma_f32 v[140:141], v[140:141], s[98:99], v[244:245]
	v_pk_fma_f32 v[142:143], v[142:143], s[98:99], v[244:245]
	v_pk_mul_f32 v[140:141], v[132:133], v[140:141]
	v_pk_mul_f32 v[142:143], v[134:135], v[142:143]
	v_exp_f32_e32 v140, v140
	v_exp_f32_e32 v141, v141
	v_exp_f32_e32 v142, v142
	v_exp_f32_e32 v143, v143
	v_pk_add_f32 v[140:141], v[140:141], s[100:101]
	v_pk_add_f32 v[142:143], v[142:143], s[100:101]
	v_rcp_f32_e32 v140, v140
	v_rcp_f32_e32 v141, v141
	v_rcp_f32_e32 v142, v142
	v_rcp_f32_e32 v143, v143
	v_pk_mul_f32 v[140:141], v[132:133], v[140:141]
	v_pk_mul_f32 v[142:143], v[134:135], v[142:143]
	v_pk_mul_f32 v[140:141], v[140:141], v[136:137]
	v_pk_mul_f32 v[142:143], v[142:143], v[138:139]
	v_cvt_pk_bf16_f32 v250, v140, v141
	v_cvt_pk_bf16_f32 v251, v142, v143
	v_pk_fma_f32 v[132:133], v[76:77], v[190:191], v[178:179]
	v_pk_fma_f32 v[136:137], v[64:65], v[206:207], v[194:195]
	v_pk_fma_f32 v[134:135], v[78:79], v[192:193], v[180:181]
	v_pk_fma_f32 v[138:139], v[66:67], v[208:209], v[196:197]
	v_fmac_f32_dpp v132, v76, v186 row_shr:1 row_mask:0xf bank_mask:0xf
	v_fmac_f32_dpp v133, v77, v187 row_shr:1 row_mask:0xf bank_mask:0xf
	v_fmac_f32_dpp v134, v78, v188 row_shr:1 row_mask:0xf bank_mask:0xf
	v_fmac_f32_dpp v135, v79, v189 row_shr:1 row_mask:0xf bank_mask:0xf
	v_fmac_f32_dpp v136, v64, v202 row_shr:1 row_mask:0xf bank_mask:0xf
	v_fmac_f32_dpp v137, v65, v203 row_shr:1 row_mask:0xf bank_mask:0xf
	v_fmac_f32_dpp v138, v66, v204 row_shr:1 row_mask:0xf bank_mask:0xf
	v_fmac_f32_dpp v139, v67, v205 row_shr:1 row_mask:0xf bank_mask:0xf
; __device__ __forceinline__ unsigned pk2(float lo, float hi) { unsigned r; asm("v_cvt_pk_bf16_f32 %0, %1, %2" : "=v"(r) : "v"(lo), "v"(hi)); return r; }
; __device__ __forceinline__ float gelu_tanh(float x) { const float y = 1.5957691216f * (x + 0.044715f * x * x * x); return x * __builtin_amdgcn_rcpf(1.0f + __expf(-y)); }
; __device__ __forceinline__ float dpp_shr1(float old, float src) { return __int_as_float(__builtin_amdgcn_update_dpp(__float_as_int(old), __float_as_int(src), 0x111, 0xf, 0xf, false)); }
; __device__ __forceinline__ float dpp_shr2(float old, float src) { return __int_as_float(__builtin_amdgcn_update_dpp(__float_as_int(old), __float_as_int(src), 0x112, 0xf, 0xf, false)); }
; __device__ __forceinline__ float dpp_ror1(float src) { return __int_as_float(__builtin_amdgcn_update_dpp(0, __float_as_int(src), 0x121, 0xf, 0xf, false)); }
;     __device__ __forceinline__ void operator()(const f32x4 (&acc)[2][2][4][2], const Unit& u, int wr, int wc, int fr, int fq) const {
;     ...
;                 for (int m = 0; m < 4; ++m) { const int row = row0 + ai * HALF + m * 16;
;                     const f32x4 g0 = acc[ai][0][m][n], v0 = acc[ai][1][m][n];
;                     f32x4 gp = (f32x4){0.f, 0.f, 0.f, 0.f}, vp = gp;
;                     if (m > 0) { gp = acc[ai][0][m > 0 ? m - 1 : 0][n]; vp = acc[ai][1][m > 0 ? m - 1 : 0][n]; }
;                     f32x4 f;
; #pragma unroll
;                     for (int j = 0; j < 4; ++j) {
;                         const float g1 = dpp_shr1(dpp_ror1(gp[j]), g0[j]), g2 = dpp_shr2(dpp_ror2(gp[j]), g0[j]);
;                         const float v1 = dpp_shr1(dpp_ror1(vp[j]), v0[j]), v2 = dpp_shr2(dpp_ror2(vp[j]), v0[j]);
;                         const float cg_ = bg[j] + g2 * wg0[j] + g1 * wg1[j] + g0[j] * wg2[j];
;                         const float cv_ = bv[j] + v2 * wv0[j] + v1 * wv1[j] + v0[j] * wv2[j];
;                         f[j] = gelu_tanh(cg_) * cv_; }
;                     u32x2 w; w.x = pk2(f[0], f[1]); w.y = pk2(f[2], f[3]);
;                     if (n == 0) res0[ai * 4 + m] = w;
;                     else if (m > 0 || fr >= 2) { u32x4 w4; w4.x = res0[ai * 4 + m].x; w4.y = res0[ai * 4 + m].y; w4.z = w.x; w4.w = w.y; *(u32x4*)(F + (size_t)row * DFF + j0) = w4; }
	v_fmac_f32_dpp v132, v92, v186 row_shl:15 row_mask:0xf bank_mask:0xf
	v_fmac_f32_dpp v133, v93, v187 row_shl:15 row_mask:0xf bank_mask:0xf
	v_fmac_f32_dpp v134, v94, v188 row_shl:15 row_mask:0xf bank_mask:0xf
	v_fmac_f32_dpp v135, v95, v189 row_shl:15 row_mask:0xf bank_mask:0xf
	v_fmac_f32_dpp v136, v72, v202 row_shl:15 row_mask:0xf bank_mask:0xf
	v_fmac_f32_dpp v137, v73, v203 row_shl:15 row_mask:0xf bank_mask:0xf
	v_fmac_f32_dpp v138, v74, v204 row_shl:15 row_mask:0xf bank_mask:0xf
	v_fmac_f32_dpp v139, v75, v205 row_shl:15 row_mask:0xf bank_mask:0xf
	v_fmac_f32_dpp v132, v76, v182 row_shr:2 row_mask:0xf bank_mask:0xf
	v_fmac_f32_dpp v133, v77, v183 row_shr:2 row_mask:0xf bank_mask:0xf
	v_fmac_f32_dpp v134, v78, v184 row_shr:2 row_mask:0xf bank_mask:0xf
	v_fmac_f32_dpp v135, v79, v185 row_shr:2 row_mask:0xf bank_mask:0xf
	v_fmac_f32_dpp v136, v64, v198 row_shr:2 row_mask:0xf bank_mask:0xf
	v_fmac_f32_dpp v137, v65, v199 row_shr:2 row_mask:0xf bank_mask:0xf
	v_fmac_f32_dpp v138, v66, v200 row_shr:2 row_mask:0xf bank_mask:0xf
	v_fmac_f32_dpp v139, v67, v201 row_shr:2 row_mask:0xf bank_mask:0xf
	v_fmac_f32_dpp v132, v92, v182 row_shl:14 row_mask:0xf bank_mask:0xf
	v_fmac_f32_dpp v133, v93, v183 row_shl:14 row_mask:0xf bank_mask:0xf
	v_fmac_f32_dpp v134, v94, v184 row_shl:14 row_mask:0xf bank_mask:0xf
	v_fmac_f32_dpp v135, v95, v185 row_shl:14 row_mask:0xf bank_mask:0xf
	v_fmac_f32_dpp v136, v72, v198 row_shl:14 row_mask:0xf bank_mask:0xf
	v_fmac_f32_dpp v137, v73, v199 row_shl:14 row_mask:0xf bank_mask:0xf
	v_fmac_f32_dpp v138, v74, v200 row_shl:14 row_mask:0xf bank_mask:0xf
	v_fmac_f32_dpp v139, v75, v201 row_shl:14 row_mask:0xf bank_mask:0xf
	v_pk_mul_f32 v[140:141], v[132:133], v[132:133]
	v_pk_mul_f32 v[142:143], v[134:135], v[134:135]
	v_pk_fma_f32 v[140:141], v[140:141], s[98:99], v[244:245]
	v_pk_fma_f32 v[142:143], v[142:143], s[98:99], v[244:245]
	v_pk_mul_f32 v[140:141], v[132:133], v[140:141]
	v_pk_mul_f32 v[142:143], v[134:135], v[142:143]
	v_exp_f32_e32 v140, v140
	v_exp_f32_e32 v141, v141
	v_exp_f32_e32 v142, v142
	v_exp_f32_e32 v143, v143
	v_pk_add_f32 v[140:141], v[140:141], s[100:101]
	v_pk_add_f32 v[142:143], v[142:143], s[100:101]
	v_rcp_f32_e32 v140, v140
	v_rcp_f32_e32 v141, v141
	v_rcp_f32_e32 v142, v142
	v_rcp_f32_e32 v143, v143
	v_pk_mul_f32 v[140:141], v[132:133], v[140:141]
	v_pk_mul_f32 v[142:143], v[134:135], v[142:143]
	v_pk_mul_f32 v[140:141], v[140:141], v[136:137]
	v_pk_mul_f32 v[142:143], v[142:143], v[138:139]
	v_cvt_pk_bf16_f32 v252, v140, v141
	v_cvt_pk_bf16_f32 v253, v142, v143
	v_add_u32_e32 v144, 0x30, v248
	v_mad_u64_u32 v[144:145], vcc, v144, s4, v[242:243]
	global_store_dwordx4 v[144:145], v[250:253], off nt
	v_pk_fma_f32 v[132:133], v[60:61], v[158:159], v[146:147]
	v_pk_fma_f32 v[136:137], v[48:49], v[174:175], v[162:163]
	v_pk_fma_f32 v[134:135], v[62:63], v[160:161], v[148:149]
	v_pk_fma_f32 v[138:139], v[50:51], v[176:177], v[164:165]
	v_fmac_f32_dpp v132, v60, v154 row_shr:1 row_mask:0xf bank_mask:0xf
	v_fmac_f32_dpp v133, v61, v155 row_shr:1 row_mask:0xf bank_mask:0xf
	v_fmac_f32_dpp v134, v62, v156 row_shr:1 row_mask:0xf bank_mask:0xf
	v_fmac_f32_dpp v135, v63, v157 row_shr:1 row_mask:0xf bank_mask:0xf
	v_fmac_f32_dpp v136, v48, v170 row_shr:1 row_mask:0xf bank_mask:0xf
	v_fmac_f32_dpp v137, v49, v171 row_shr:1 row_mask:0xf bank_mask:0xf
	v_fmac_f32_dpp v138, v50, v172 row_shr:1 row_mask:0xf bank_mask:0xf
	v_fmac_f32_dpp v139, v51, v173 row_shr:1 row_mask:0xf bank_mask:0xf
	v_fmac_f32_dpp v132, v60, v150 row_shr:2 row_mask:0xf bank_mask:0xf
	v_fmac_f32_dpp v133, v61, v151 row_shr:2 row_mask:0xf bank_mask:0xf
	v_fmac_f32_dpp v134, v62, v152 row_shr:2 row_mask:0xf bank_mask:0xf
	v_fmac_f32_dpp v135, v63, v153 row_shr:2 row_mask:0xf bank_mask:0xf
	v_fmac_f32_dpp v136, v48, v166 row_shr:2 row_mask:0xf bank_mask:0xf
	v_fmac_f32_dpp v137, v49, v167 row_shr:2 row_mask:0xf bank_mask:0xf
	v_fmac_f32_dpp v138, v50, v168 row_shr:2 row_mask:0xf bank_mask:0xf
	v_fmac_f32_dpp v139, v51, v169 row_shr:2 row_mask:0xf bank_mask:0xf
	v_pk_mul_f32 v[140:141], v[132:133], v[132:133]
	v_pk_mul_f32 v[142:143], v[134:135], v[134:135]
	v_pk_fma_f32 v[140:141], v[140:141], s[98:99], v[244:245]
	v_pk_fma_f32 v[142:143], v[142:143], s[98:99], v[244:245]
	v_pk_mul_f32 v[140:141], v[132:133], v[140:141]
	v_pk_mul_f32 v[142:143], v[134:135], v[142:143]
	v_exp_f32_e32 v140, v140
	v_exp_f32_e32 v141, v141
	v_exp_f32_e32 v142, v142
	v_exp_f32_e32 v143, v143
	v_pk_add_f32 v[140:141], v[140:141], s[100:101]
	v_pk_add_f32 v[142:143], v[142:143], s[100:101]
	v_rcp_f32_e32 v140, v140
	v_rcp_f32_e32 v141, v141
	v_rcp_f32_e32 v142, v142
	v_rcp_f32_e32 v143, v143
	v_pk_mul_f32 v[140:141], v[132:133], v[140:141]
	v_pk_mul_f32 v[142:143], v[134:135], v[142:143]
	v_pk_mul_f32 v[140:141], v[140:141], v[136:137]
	v_pk_mul_f32 v[142:143], v[142:143], v[138:139]
	v_cvt_pk_bf16_f32 v128, v140, v141
	v_cvt_pk_bf16_f32 v129, v142, v143
	v_pk_fma_f32 v[132:133], v[56:57], v[190:191], v[178:179]
	v_pk_fma_f32 v[136:137], v[40:41], v[206:207], v[194:195]
	v_pk_fma_f32 v[134:135], v[58:59], v[192:193], v[180:181]
	v_pk_fma_f32 v[138:139], v[42:43], v[208:209], v[196:197]
	v_fmac_f32_dpp v132, v56, v186 row_shr:1 row_mask:0xf bank_mask:0xf
	v_fmac_f32_dpp v133, v57, v187 row_shr:1 row_mask:0xf bank_mask:0xf
	v_fmac_f32_dpp v134, v58, v188 row_shr:1 row_mask:0xf bank_mask:0xf
	v_fmac_f32_dpp v135, v59, v189 row_shr:1 row_mask:0xf bank_mask:0xf
	v_fmac_f32_dpp v136, v40, v202 row_shr:1 row_mask:0xf bank_mask:0xf
	v_fmac_f32_dpp v137, v41, v203 row_shr:1 row_mask:0xf bank_mask:0xf
	v_fmac_f32_dpp v138, v42, v204 row_shr:1 row_mask:0xf bank_mask:0xf
; __device__ __forceinline__ unsigned pk2(float lo, float hi) { unsigned r; asm("v_cvt_pk_bf16_f32 %0, %1, %2" : "=v"(r) : "v"(lo), "v"(hi)); return r; }
; __device__ __forceinline__ float gelu_tanh(float x) { const float y = 1.5957691216f * (x + 0.044715f * x * x * x); return x * __builtin_amdgcn_rcpf(1.0f + __expf(-y)); }
; __device__ __forceinline__ float dpp_shr1(float old, float src) { return __int_as_float(__builtin_amdgcn_update_dpp(__float_as_int(old), __float_as_int(src), 0x111, 0xf, 0xf, false)); }
; __device__ __forceinline__ float dpp_shr2(float old, float src) { return __int_as_float(__builtin_amdgcn_update_dpp(__float_as_int(old), __float_as_int(src), 0x112, 0xf, 0xf, false)); }
; __device__ __forceinline__ float dpp_ror1(float src) { return __int_as_float(__builtin_amdgcn_update_dpp(0, __float_as_int(src), 0x121, 0xf, 0xf, false)); }
;     __device__ __forceinline__ void operator()(const f32x4 (&acc)[2][2][4][2], const Unit& u, int wr, int wc, int fr, int fq) const {
;     ...
;                 for (int m = 0; m < 4; ++m) { const int row = row0 + ai * HALF + m * 16;
;                     const f32x4 g0 = acc[ai][0][m][n], v0 = acc[ai][1][m][n];
;                     f32x4 gp = (f32x4){0.f, 0.f, 0.f, 0.f}, vp = gp;
;                     if (m > 0) { gp = acc[ai][0][m > 0 ? m - 1 : 0][n]; vp = acc[ai][1][m > 0 ? m - 1 : 0][n]; }
;                     f32x4 f;
; #pragma unroll
;                     for (int j = 0; j < 4; ++j) {
;                         const float g1 = dpp_shr1(dpp_ror1(gp[j]), g0[j]), g2 = dpp_shr2(dpp_ror2(gp[j]), g0[j]);
;                         const float v1 = dpp_shr1(dpp_ror1(vp[j]), v0[j]), v2 = dpp_shr2(dpp_ror2(vp[j]), v0[j]);
;                         const float cg_ = bg[j] + g2 * wg0[j] + g1 * wg1[j] + g0[j] * wg2[j];
;                         const float cv_ = bv[j] + v2 * wv0[j] + v1 * wv1[j] + v0[j] * wv2[j];
;                         f[j] = gelu_tanh(cg_) * cv_; }
;                     u32x2 w; w.x = pk2(f[0], f[1]); w.y = pk2(f[2], f[3]);
;                     if (n == 0) res0[ai * 4 + m] = w;
;                     else if (m > 0 || fr >= 2) { u32x4 w4; w4.x = res0[ai * 4 + m].x; w4.y = res0[ai * 4 + m].y; w4.z = w.x; w4.w = w.y; *(u32x4*)(F + (size_t)row * DFF + j0) = w4; }
	v_fmac_f32_dpp v139, v43, v205 row_shr:1 row_mask:0xf bank_mask:0xf
	v_fmac_f32_dpp v132, v56, v182 row_shr:2 row_mask:0xf bank_mask:0xf
	v_fmac_f32_dpp v133, v57, v183 row_shr:2 row_mask:0xf bank_mask:0xf
	v_fmac_f32_dpp v134, v58, v184 row_shr:2 row_mask:0xf bank_mask:0xf
	v_fmac_f32_dpp v135, v59, v185 row_shr:2 row_mask:0xf bank_mask:0xf
	v_fmac_f32_dpp v136, v40, v198 row_shr:2 row_mask:0xf bank_mask:0xf
	v_fmac_f32_dpp v137, v41, v199 row_shr:2 row_mask:0xf bank_mask:0xf
	v_fmac_f32_dpp v138, v42, v200 row_shr:2 row_mask:0xf bank_mask:0xf
	v_fmac_f32_dpp v139, v43, v201 row_shr:2 row_mask:0xf bank_mask:0xf
	v_pk_mul_f32 v[140:141], v[132:133], v[132:133]
	v_pk_mul_f32 v[142:143], v[134:135], v[134:135]
	v_pk_fma_f32 v[140:141], v[140:141], s[98:99], v[244:245]
	v_pk_fma_f32 v[142:143], v[142:143], s[98:99], v[244:245]
	v_pk_mul_f32 v[140:141], v[132:133], v[140:141]
	v_pk_mul_f32 v[142:143], v[134:135], v[142:143]
	v_exp_f32_e32 v140, v140
	v_exp_f32_e32 v141, v141
	v_exp_f32_e32 v142, v142
	v_exp_f32_e32 v143, v143
	v_pk_add_f32 v[140:141], v[140:141], s[100:101]
	v_pk_add_f32 v[142:143], v[142:143], s[100:101]
	v_rcp_f32_e32 v140, v140
	v_rcp_f32_e32 v141, v141
	v_rcp_f32_e32 v142, v142
	v_rcp_f32_e32 v143, v143
	v_pk_mul_f32 v[140:141], v[132:133], v[140:141]
	v_pk_mul_f32 v[142:143], v[134:135], v[142:143]
	v_pk_mul_f32 v[140:141], v[140:141], v[136:137]
	v_pk_mul_f32 v[142:143], v[142:143], v[138:139]
	v_cvt_pk_bf16_f32 v130, v140, v141
	v_cvt_pk_bf16_f32 v131, v142, v143
	s_and_saveexec_b64 s[42:43], s[8:9]
	v_add_u32_e32 v144, 0x80, v248
	v_mad_u64_u32 v[144:145], vcc, v144, s4, v[242:243]
	global_store_dwordx4 v[144:145], v[128:131], off nt
	s_or_b64 exec, exec, s[42:43]
	s_nop 4
	v_pk_fma_f32 v[132:133], v[52:53], v[158:159], v[146:147]
	v_pk_fma_f32 v[136:137], v[32:33], v[174:175], v[162:163]
	v_pk_fma_f32 v[134:135], v[54:55], v[160:161], v[148:149]
	v_pk_fma_f32 v[138:139], v[34:35], v[176:177], v[164:165]
	v_fmac_f32_dpp v132, v52, v154 row_shr:1 row_mask:0xf bank_mask:0xf
	v_fmac_f32_dpp v133, v53, v155 row_shr:1 row_mask:0xf bank_mask:0xf
	v_fmac_f32_dpp v134, v54, v156 row_shr:1 row_mask:0xf bank_mask:0xf
	v_fmac_f32_dpp v135, v55, v157 row_shr:1 row_mask:0xf bank_mask:0xf
	v_fmac_f32_dpp v136, v32, v170 row_shr:1 row_mask:0xf bank_mask:0xf
	v_fmac_f32_dpp v137, v33, v171 row_shr:1 row_mask:0xf bank_mask:0xf
	v_fmac_f32_dpp v138, v34, v172 row_shr:1 row_mask:0xf bank_mask:0xf
	v_fmac_f32_dpp v139, v35, v173 row_shr:1 row_mask:0xf bank_mask:0xf
	v_fmac_f32_dpp v132, v60, v154 row_shl:15 row_mask:0xf bank_mask:0xf
	v_fmac_f32_dpp v133, v61, v155 row_shl:15 row_mask:0xf bank_mask:0xf
	v_fmac_f32_dpp v134, v62, v156 row_shl:15 row_mask:0xf bank_mask:0xf
	v_fmac_f32_dpp v135, v63, v157 row_shl:15 row_mask:0xf bank_mask:0xf
	v_fmac_f32_dpp v136, v48, v170 row_shl:15 row_mask:0xf bank_mask:0xf
	v_fmac_f32_dpp v137, v49, v171 row_shl:15 row_mask:0xf bank_mask:0xf
	v_fmac_f32_dpp v138, v50, v172 row_shl:15 row_mask:0xf bank_mask:0xf
	v_fmac_f32_dpp v139, v51, v173 row_shl:15 row_mask:0xf bank_mask:0xf
	v_fmac_f32_dpp v132, v52, v150 row_shr:2 row_mask:0xf bank_mask:0xf
	v_fmac_f32_dpp v133, v53, v151 row_shr:2 row_mask:0xf bank_mask:0xf
	v_fmac_f32_dpp v134, v54, v152 row_shr:2 row_mask:0xf bank_mask:0xf
	v_fmac_f32_dpp v135, v55, v153 row_shr:2 row_mask:0xf bank_mask:0xf
	v_fmac_f32_dpp v136, v32, v166 row_shr:2 row_mask:0xf bank_mask:0xf
	v_fmac_f32_dpp v137, v33, v167 row_shr:2 row_mask:0xf bank_mask:0xf
	v_fmac_f32_dpp v138, v34, v168 row_shr:2 row_mask:0xf bank_mask:0xf
	v_fmac_f32_dpp v139, v35, v169 row_shr:2 row_mask:0xf bank_mask:0xf
	v_fmac_f32_dpp v132, v60, v150 row_shl:14 row_mask:0xf bank_mask:0xf
	v_fmac_f32_dpp v133, v61, v151 row_shl:14 row_mask:0xf bank_mask:0xf
	v_fmac_f32_dpp v134, v62, v152 row_shl:14 row_mask:0xf bank_mask:0xf
	v_fmac_f32_dpp v135, v63, v153 row_shl:14 row_mask:0xf bank_mask:0xf
	v_fmac_f32_dpp v136, v48, v166 row_shl:14 row_mask:0xf bank_mask:0xf
	v_fmac_f32_dpp v137, v49, v167 row_shl:14 row_mask:0xf bank_mask:0xf
	v_fmac_f32_dpp v138, v50, v168 row_shl:14 row_mask:0xf bank_mask:0xf
	v_fmac_f32_dpp v139, v51, v169 row_shl:14 row_mask:0xf bank_mask:0xf
	v_pk_mul_f32 v[140:141], v[132:133], v[132:133]
	v_pk_mul_f32 v[142:143], v[134:135], v[134:135]
	v_pk_fma_f32 v[140:141], v[140:141], s[98:99], v[244:245]
	v_pk_fma_f32 v[142:143], v[142:143], s[98:99], v[244:245]
	v_pk_mul_f32 v[140:141], v[132:133], v[140:141]
	v_pk_mul_f32 v[142:143], v[134:135], v[142:143]
	v_exp_f32_e32 v140, v140
	v_exp_f32_e32 v141, v141
	v_exp_f32_e32 v142, v142
	v_exp_f32_e32 v143, v143
	v_pk_add_f32 v[140:141], v[140:141], s[100:101]
	v_pk_add_f32 v[142:143], v[142:143], s[100:101]
	v_rcp_f32_e32 v140, v140
	v_rcp_f32_e32 v141, v141
	v_rcp_f32_e32 v142, v142
	v_rcp_f32_e32 v143, v143
	v_pk_mul_f32 v[140:141], v[132:133], v[140:141]
	v_pk_mul_f32 v[142:143], v[134:135], v[142:143]
	v_pk_mul_f32 v[140:141], v[140:141], v[136:137]
	v_pk_mul_f32 v[142:143], v[142:143], v[138:139]
	v_cvt_pk_bf16_f32 v250, v140, v141
	v_cvt_pk_bf16_f32 v251, v142, v143
	v_pk_fma_f32 v[132:133], v[44:45], v[190:191], v[178:179]
	v_pk_fma_f32 v[136:137], v[24:25], v[206:207], v[194:195]
	v_pk_fma_f32 v[134:135], v[46:47], v[192:193], v[180:181]
	v_pk_fma_f32 v[138:139], v[26:27], v[208:209], v[196:197]
	v_fmac_f32_dpp v132, v44, v186 row_shr:1 row_mask:0xf bank_mask:0xf
	v_fmac_f32_dpp v133, v45, v187 row_shr:1 row_mask:0xf bank_mask:0xf
	v_fmac_f32_dpp v134, v46, v188 row_shr:1 row_mask:0xf bank_mask:0xf
	v_fmac_f32_dpp v135, v47, v189 row_shr:1 row_mask:0xf bank_mask:0xf
	v_fmac_f32_dpp v136, v24, v202 row_shr:1 row_mask:0xf bank_mask:0xf
; __device__ __forceinline__ unsigned pk2(float lo, float hi) { unsigned r; asm("v_cvt_pk_bf16_f32 %0, %1, %2" : "=v"(r) : "v"(lo), "v"(hi)); return r; }
; __device__ __forceinline__ float gelu_tanh(float x) { const float y = 1.5957691216f * (x + 0.044715f * x * x * x); return x * __builtin_amdgcn_rcpf(1.0f + __expf(-y)); }
; __device__ __forceinline__ float dpp_shr1(float old, float src) { return __int_as_float(__builtin_amdgcn_update_dpp(__float_as_int(old), __float_as_int(src), 0x111, 0xf, 0xf, false)); }
; __device__ __forceinline__ float dpp_shr2(float old, float src) { return __int_as_float(__builtin_amdgcn_update_dpp(__float_as_int(old), __float_as_int(src), 0x112, 0xf, 0xf, false)); }
; __device__ __forceinline__ float dpp_ror1(float src) { return __int_as_float(__builtin_amdgcn_update_dpp(0, __float_as_int(src), 0x121, 0xf, 0xf, false)); }
;     __device__ __forceinline__ void operator()(const f32x4 (&acc)[2][2][4][2], const Unit& u, int wr, int wc, int fr, int fq) const {
;     ...
;                 for (int m = 0; m < 4; ++m) { const int row = row0 + ai * HALF + m * 16;
;                     const f32x4 g0 = acc[ai][0][m][n], v0 = acc[ai][1][m][n];
;                     f32x4 gp = (f32x4){0.f, 0.f, 0.f, 0.f}, vp = gp;
;                     if (m > 0) { gp = acc[ai][0][m > 0 ? m - 1 : 0][n]; vp = acc[ai][1][m > 0 ? m - 1 : 0][n]; }
;                     f32x4 f;
; #pragma unroll
;                     for (int j = 0; j < 4; ++j) {
;                         const float g1 = dpp_shr1(dpp_ror1(gp[j]), g0[j]), g2 = dpp_shr2(dpp_ror2(gp[j]), g0[j]);
;                         const float v1 = dpp_shr1(dpp_ror1(vp[j]), v0[j]), v2 = dpp_shr2(dpp_ror2(vp[j]), v0[j]);
;                         const float cg_ = bg[j] + g2 * wg0[j] + g1 * wg1[j] + g0[j] * wg2[j];
;                         const float cv_ = bv[j] + v2 * wv0[j] + v1 * wv1[j] + v0[j] * wv2[j];
;                         f[j] = gelu_tanh(cg_) * cv_; }
;                     u32x2 w; w.x = pk2(f[0], f[1]); w.y = pk2(f[2], f[3]);
;                     if (n == 0) res0[ai * 4 + m] = w;
;                     else if (m > 0 || fr >= 2) { u32x4 w4; w4.x = res0[ai * 4 + m].x; w4.y = res0[ai * 4 + m].y; w4.z = w.x; w4.w = w.y; *(u32x4*)(F + (size_t)row * DFF + j0) = w4; }
	v_fmac_f32_dpp v137, v25, v203 row_shr:1 row_mask:0xf bank_mask:0xf
	v_fmac_f32_dpp v138, v26, v204 row_shr:1 row_mask:0xf bank_mask:0xf
	v_fmac_f32_dpp v139, v27, v205 row_shr:1 row_mask:0xf bank_mask:0xf
	v_fmac_f32_dpp v132, v56, v186 row_shl:15 row_mask:0xf bank_mask:0xf
	v_fmac_f32_dpp v133, v57, v187 row_shl:15 row_mask:0xf bank_mask:0xf
	v_fmac_f32_dpp v134, v58, v188 row_shl:15 row_mask:0xf bank_mask:0xf
	v_fmac_f32_dpp v135, v59, v189 row_shl:15 row_mask:0xf bank_mask:0xf
	v_fmac_f32_dpp v136, v40, v202 row_shl:15 row_mask:0xf bank_mask:0xf
	v_fmac_f32_dpp v137, v41, v203 row_shl:15 row_mask:0xf bank_mask:0xf
	v_fmac_f32_dpp v138, v42, v204 row_shl:15 row_mask:0xf bank_mask:0xf
	v_fmac_f32_dpp v139, v43, v205 row_shl:15 row_mask:0xf bank_mask:0xf
	v_fmac_f32_dpp v132, v44, v182 row_shr:2 row_mask:0xf bank_mask:0xf
	v_fmac_f32_dpp v133, v45, v183 row_shr:2 row_mask:0xf bank_mask:0xf
	v_fmac_f32_dpp v134, v46, v184 row_shr:2 row_mask:0xf bank_mask:0xf
	v_fmac_f32_dpp v135, v47, v185 row_shr:2 row_mask:0xf bank_mask:0xf
	v_fmac_f32_dpp v136, v24, v198 row_shr:2 row_mask:0xf bank_mask:0xf
	v_fmac_f32_dpp v137, v25, v199 row_shr:2 row_mask:0xf bank_mask:0xf
	v_fmac_f32_dpp v138, v26, v200 row_shr:2 row_mask:0xf bank_mask:0xf
	v_fmac_f32_dpp v139, v27, v201 row_shr:2 row_mask:0xf bank_mask:0xf
	v_fmac_f32_dpp v132, v56, v182 row_shl:14 row_mask:0xf bank_mask:0xf
	v_fmac_f32_dpp v133, v57, v183 row_shl:14 row_mask:0xf bank_mask:0xf
	v_fmac_f32_dpp v134, v58, v184 row_shl:14 row_mask:0xf bank_mask:0xf
	v_fmac_f32_dpp v135, v59, v185 row_shl:14 row_mask:0xf bank_mask:0xf
	v_fmac_f32_dpp v136, v40, v198 row_shl:14 row_mask:0xf bank_mask:0xf
	v_fmac_f32_dpp v137, v41, v199 row_shl:14 row_mask:0xf bank_mask:0xf
	v_fmac_f32_dpp v138, v42, v200 row_shl:14 row_mask:0xf bank_mask:0xf
	v_fmac_f32_dpp v139, v43, v201 row_shl:14 row_mask:0xf bank_mask:0xf
	v_pk_mul_f32 v[140:141], v[132:133], v[132:133]
	v_pk_mul_f32 v[142:143], v[134:135], v[134:135]
	v_pk_fma_f32 v[140:141], v[140:141], s[98:99], v[244:245]
	v_pk_fma_f32 v[142:143], v[142:143], s[98:99], v[244:245]
	v_pk_mul_f32 v[140:141], v[132:133], v[140:141]
	v_pk_mul_f32 v[142:143], v[134:135], v[142:143]
	v_exp_f32_e32 v140, v140
	v_exp_f32_e32 v141, v141
	v_exp_f32_e32 v142, v142
	v_exp_f32_e32 v143, v143
	v_pk_add_f32 v[140:141], v[140:141], s[100:101]
	v_pk_add_f32 v[142:143], v[142:143], s[100:101]
	v_rcp_f32_e32 v140, v140
	v_rcp_f32_e32 v141, v141
	v_rcp_f32_e32 v142, v142
	v_rcp_f32_e32 v143, v143
	v_pk_mul_f32 v[140:141], v[132:133], v[140:141]
	v_pk_mul_f32 v[142:143], v[134:135], v[142:143]
	v_pk_mul_f32 v[140:141], v[140:141], v[136:137]
	v_pk_mul_f32 v[142:143], v[142:143], v[138:139]
	v_cvt_pk_bf16_f32 v252, v140, v141
	v_cvt_pk_bf16_f32 v253, v142, v143
	v_add_u32_e32 v144, 0x90, v248
	v_mad_u64_u32 v[144:145], vcc, v144, s4, v[242:243]
	global_store_dwordx4 v[144:145], v[250:253], off nt
	v_pk_fma_f32 v[132:133], v[36:37], v[158:159], v[146:147]
	v_pk_fma_f32 v[136:137], v[16:17], v[174:175], v[162:163]
	v_pk_fma_f32 v[134:135], v[38:39], v[160:161], v[148:149]
	v_pk_fma_f32 v[138:139], v[18:19], v[176:177], v[164:165]
	v_fmac_f32_dpp v132, v36, v154 row_shr:1 row_mask:0xf bank_mask:0xf
	v_fmac_f32_dpp v133, v37, v155 row_shr:1 row_mask:0xf bank_mask:0xf
	v_fmac_f32_dpp v134, v38, v156 row_shr:1 row_mask:0xf bank_mask:0xf
	v_fmac_f32_dpp v135, v39, v157 row_shr:1 row_mask:0xf bank_mask:0xf
	v_fmac_f32_dpp v136, v16, v170 row_shr:1 row_mask:0xf bank_mask:0xf
	v_fmac_f32_dpp v137, v17, v171 row_shr:1 row_mask:0xf bank_mask:0xf
	v_fmac_f32_dpp v138, v18, v172 row_shr:1 row_mask:0xf bank_mask:0xf
	v_fmac_f32_dpp v139, v19, v173 row_shr:1 row_mask:0xf bank_mask:0xf
	v_fmac_f32_dpp v132, v52, v154 row_shl:15 row_mask:0xf bank_mask:0xf
	v_fmac_f32_dpp v133, v53, v155 row_shl:15 row_mask:0xf bank_mask:0xf
	v_fmac_f32_dpp v134, v54, v156 row_shl:15 row_mask:0xf bank_mask:0xf
	v_fmac_f32_dpp v135, v55, v157 row_shl:15 row_mask:0xf bank_mask:0xf
	v_fmac_f32_dpp v136, v32, v170 row_shl:15 row_mask:0xf bank_mask:0xf
	v_fmac_f32_dpp v137, v33, v171 row_shl:15 row_mask:0xf bank_mask:0xf
	v_fmac_f32_dpp v138, v34, v172 row_shl:15 row_mask:0xf bank_mask:0xf
	v_fmac_f32_dpp v139, v35, v173 row_shl:15 row_mask:0xf bank_mask:0xf
	v_fmac_f32_dpp v132, v36, v150 row_shr:2 row_mask:0xf bank_mask:0xf
	v_fmac_f32_dpp v133, v37, v151 row_shr:2 row_mask:0xf bank_mask:0xf
	v_fmac_f32_dpp v134, v38, v152 row_shr:2 row_mask:0xf bank_mask:0xf
	v_fmac_f32_dpp v135, v39, v153 row_shr:2 row_mask:0xf bank_mask:0xf
	v_fmac_f32_dpp v136, v16, v166 row_shr:2 row_mask:0xf bank_mask:0xf
	v_fmac_f32_dpp v137, v17, v167 row_shr:2 row_mask:0xf bank_mask:0xf
	v_fmac_f32_dpp v138, v18, v168 row_shr:2 row_mask:0xf bank_mask:0xf
	v_fmac_f32_dpp v139, v19, v169 row_shr:2 row_mask:0xf bank_mask:0xf
	v_fmac_f32_dpp v132, v52, v150 row_shl:14 row_mask:0xf bank_mask:0xf
	v_fmac_f32_dpp v133, v53, v151 row_shl:14 row_mask:0xf bank_mask:0xf
	v_fmac_f32_dpp v134, v54, v152 row_shl:14 row_mask:0xf bank_mask:0xf
	v_fmac_f32_dpp v135, v55, v153 row_shl:14 row_mask:0xf bank_mask:0xf
	v_fmac_f32_dpp v136, v32, v166 row_shl:14 row_mask:0xf bank_mask:0xf
	v_fmac_f32_dpp v137, v33, v167 row_shl:14 row_mask:0xf bank_mask:0xf
	v_fmac_f32_dpp v138, v34, v168 row_shl:14 row_mask:0xf bank_mask:0xf
	v_fmac_f32_dpp v139, v35, v169 row_shl:14 row_mask:0xf bank_mask:0xf
	v_pk_mul_f32 v[140:141], v[132:133], v[132:133]
	v_pk_mul_f32 v[142:143], v[134:135], v[134:135]
	v_pk_fma_f32 v[140:141], v[140:141], s[98:99], v[244:245]
	v_pk_fma_f32 v[142:143], v[142:143], s[98:99], v[244:245]
	v_pk_mul_f32 v[140:141], v[132:133], v[140:141]
; __device__ __forceinline__ unsigned pk2(float lo, float hi) { unsigned r; asm("v_cvt_pk_bf16_f32 %0, %1, %2" : "=v"(r) : "v"(lo), "v"(hi)); return r; }
; __device__ __forceinline__ float gelu_tanh(float x) { const float y = 1.5957691216f * (x + 0.044715f * x * x * x); return x * __builtin_amdgcn_rcpf(1.0f + __expf(-y)); }
; __device__ __forceinline__ float dpp_shr1(float old, float src) { return __int_as_float(__builtin_amdgcn_update_dpp(__float_as_int(old), __float_as_int(src), 0x111, 0xf, 0xf, false)); }
; __device__ __forceinline__ float dpp_shr2(float old, float src) { return __int_as_float(__builtin_amdgcn_update_dpp(__float_as_int(old), __float_as_int(src), 0x112, 0xf, 0xf, false)); }
; __device__ __forceinline__ float dpp_ror1(float src) { return __int_as_float(__builtin_amdgcn_update_dpp(0, __float_as_int(src), 0x121, 0xf, 0xf, false)); }
;     __device__ __forceinline__ void operator()(const f32x4 (&acc)[2][2][4][2], const Unit& u, int wr, int wc, int fr, int fq) const {
;     ...
;                 for (int m = 0; m < 4; ++m) { const int row = row0 + ai * HALF + m * 16;
;                     const f32x4 g0 = acc[ai][0][m][n], v0 = acc[ai][1][m][n];
;                     f32x4 gp = (f32x4){0.f, 0.f, 0.f, 0.f}, vp = gp;
;                     if (m > 0) { gp = acc[ai][0][m > 0 ? m - 1 : 0][n]; vp = acc[ai][1][m > 0 ? m - 1 : 0][n]; }
;                     f32x4 f;
; #pragma unroll
;                     for (int j = 0; j < 4; ++j) {
;                         const float g1 = dpp_shr1(dpp_ror1(gp[j]), g0[j]), g2 = dpp_shr2(dpp_ror2(gp[j]), g0[j]);
;                         const float v1 = dpp_shr1(dpp_ror1(vp[j]), v0[j]), v2 = dpp_shr2(dpp_ror2(vp[j]), v0[j]);
;                         const float cg_ = bg[j] + g2 * wg0[j] + g1 * wg1[j] + g0[j] * wg2[j];
;                         const float cv_ = bv[j] + v2 * wv0[j] + v1 * wv1[j] + v0[j] * wv2[j];
;                         f[j] = gelu_tanh(cg_) * cv_; }
;                     u32x2 w; w.x = pk2(f[0], f[1]); w.y = pk2(f[2], f[3]);
;                     if (n == 0) res0[ai * 4 + m] = w;
;                     else if (m > 0 || fr >= 2) { u32x4 w4; w4.x = res0[ai * 4 + m].x; w4.y = res0[ai * 4 + m].y; w4.z = w.x; w4.w = w.y; *(u32x4*)(F + (size_t)row * DFF + j0) = w4; }
	v_pk_mul_f32 v[142:143], v[134:135], v[142:143]
	v_exp_f32_e32 v140, v140
	v_exp_f32_e32 v141, v141
	v_exp_f32_e32 v142, v142
	v_exp_f32_e32 v143, v143
	v_pk_add_f32 v[140:141], v[140:141], s[100:101]
	v_pk_add_f32 v[142:143], v[142:143], s[100:101]
	v_rcp_f32_e32 v140, v140
	v_rcp_f32_e32 v141, v141
	v_rcp_f32_e32 v142, v142
	v_rcp_f32_e32 v143, v143
	v_pk_mul_f32 v[140:141], v[132:133], v[140:141]
	v_pk_mul_f32 v[142:143], v[134:135], v[142:143]
	v_pk_mul_f32 v[140:141], v[140:141], v[136:137]
	v_pk_mul_f32 v[142:143], v[142:143], v[138:139]
	v_cvt_pk_bf16_f32 v128, v140, v141
	v_cvt_pk_bf16_f32 v129, v142, v143
	v_pk_fma_f32 v[132:133], v[28:29], v[190:191], v[178:179]
	v_pk_fma_f32 v[136:137], v[8:9], v[206:207], v[194:195]
	v_pk_fma_f32 v[134:135], v[30:31], v[192:193], v[180:181]
	v_pk_fma_f32 v[138:139], v[10:11], v[208:209], v[196:197]
	v_fmac_f32_dpp v132, v28, v186 row_shr:1 row_mask:0xf bank_mask:0xf
	v_fmac_f32_dpp v133, v29, v187 row_shr:1 row_mask:0xf bank_mask:0xf
	v_fmac_f32_dpp v134, v30, v188 row_shr:1 row_mask:0xf bank_mask:0xf
	v_fmac_f32_dpp v135, v31, v189 row_shr:1 row_mask:0xf bank_mask:0xf
	v_fmac_f32_dpp v136, v8, v202 row_shr:1 row_mask:0xf bank_mask:0xf
	v_fmac_f32_dpp v137, v9, v203 row_shr:1 row_mask:0xf bank_mask:0xf
	v_fmac_f32_dpp v138, v10, v204 row_shr:1 row_mask:0xf bank_mask:0xf
	v_fmac_f32_dpp v139, v11, v205 row_shr:1 row_mask:0xf bank_mask:0xf
	v_fmac_f32_dpp v132, v44, v186 row_shl:15 row_mask:0xf bank_mask:0xf
	v_fmac_f32_dpp v133, v45, v187 row_shl:15 row_mask:0xf bank_mask:0xf
	v_fmac_f32_dpp v134, v46, v188 row_shl:15 row_mask:0xf bank_mask:0xf
	v_fmac_f32_dpp v135, v47, v189 row_shl:15 row_mask:0xf bank_mask:0xf
	v_fmac_f32_dpp v136, v24, v202 row_shl:15 row_mask:0xf bank_mask:0xf
	v_fmac_f32_dpp v137, v25, v203 row_shl:15 row_mask:0xf bank_mask:0xf
	v_fmac_f32_dpp v138, v26, v204 row_shl:15 row_mask:0xf bank_mask:0xf
	v_fmac_f32_dpp v139, v27, v205 row_shl:15 row_mask:0xf bank_mask:0xf
	v_fmac_f32_dpp v132, v28, v182 row_shr:2 row_mask:0xf bank_mask:0xf
	v_fmac_f32_dpp v133, v29, v183 row_shr:2 row_mask:0xf bank_mask:0xf
	v_fmac_f32_dpp v134, v30, v184 row_shr:2 row_mask:0xf bank_mask:0xf
	v_fmac_f32_dpp v135, v31, v185 row_shr:2 row_mask:0xf bank_mask:0xf
	v_fmac_f32_dpp v136, v8, v198 row_shr:2 row_mask:0xf bank_mask:0xf
	v_fmac_f32_dpp v137, v9, v199 row_shr:2 row_mask:0xf bank_mask:0xf
	v_fmac_f32_dpp v138, v10, v200 row_shr:2 row_mask:0xf bank_mask:0xf
	v_fmac_f32_dpp v139, v11, v201 row_shr:2 row_mask:0xf bank_mask:0xf
	v_fmac_f32_dpp v132, v44, v182 row_shl:14 row_mask:0xf bank_mask:0xf
	v_fmac_f32_dpp v133, v45, v183 row_shl:14 row_mask:0xf bank_mask:0xf
	v_fmac_f32_dpp v134, v46, v184 row_shl:14 row_mask:0xf bank_mask:0xf
	v_fmac_f32_dpp v135, v47, v185 row_shl:14 row_mask:0xf bank_mask:0xf
	v_fmac_f32_dpp v136, v24, v198 row_shl:14 row_mask:0xf bank_mask:0xf
	v_fmac_f32_dpp v137, v25, v199 row_shl:14 row_mask:0xf bank_mask:0xf
	v_fmac_f32_dpp v138, v26, v200 row_shl:14 row_mask:0xf bank_mask:0xf
	v_fmac_f32_dpp v139, v27, v201 row_shl:14 row_mask:0xf bank_mask:0xf
	v_pk_mul_f32 v[140:141], v[132:133], v[132:133]
	v_pk_mul_f32 v[142:143], v[134:135], v[134:135]
	v_pk_fma_f32 v[140:141], v[140:141], s[98:99], v[244:245]
	v_pk_fma_f32 v[142:143], v[142:143], s[98:99], v[244:245]
	v_pk_mul_f32 v[140:141], v[132:133], v[140:141]
	v_pk_mul_f32 v[142:143], v[134:135], v[142:143]
	v_exp_f32_e32 v140, v140
	v_exp_f32_e32 v141, v141
	v_exp_f32_e32 v142, v142
	v_exp_f32_e32 v143, v143
	v_pk_add_f32 v[140:141], v[140:141], s[100:101]
	v_pk_add_f32 v[142:143], v[142:143], s[100:101]
	v_rcp_f32_e32 v140, v140
	v_rcp_f32_e32 v141, v141
	v_rcp_f32_e32 v142, v142
	v_rcp_f32_e32 v143, v143
	v_pk_mul_f32 v[140:141], v[132:133], v[140:141]
	v_pk_mul_f32 v[142:143], v[134:135], v[142:143]
	v_pk_mul_f32 v[140:141], v[140:141], v[136:137]
	v_pk_mul_f32 v[142:143], v[142:143], v[138:139]
	v_cvt_pk_bf16_f32 v130, v140, v141
	v_cvt_pk_bf16_f32 v131, v142, v143
	v_add_u32_e32 v144, 0xa0, v248
	v_mad_u64_u32 v[144:145], vcc, v144, s4, v[242:243]
	global_store_dwordx4 v[144:145], v[128:131], off nt
	v_pk_fma_f32 v[132:133], v[20:21], v[158:159], v[146:147]
	v_pk_fma_f32 v[136:137], v[4:5], v[174:175], v[162:163]
	v_pk_fma_f32 v[134:135], v[22:23], v[160:161], v[148:149]
	v_pk_fma_f32 v[138:139], v[6:7], v[176:177], v[164:165]
	v_fmac_f32_dpp v132, v20, v154 row_shr:1 row_mask:0xf bank_mask:0xf
	v_fmac_f32_dpp v133, v21, v155 row_shr:1 row_mask:0xf bank_mask:0xf
	v_fmac_f32_dpp v134, v22, v156 row_shr:1 row_mask:0xf bank_mask:0xf
	v_fmac_f32_dpp v135, v23, v157 row_shr:1 row_mask:0xf bank_mask:0xf
	v_fmac_f32_dpp v136, v4, v170 row_shr:1 row_mask:0xf bank_mask:0xf
	v_fmac_f32_dpp v137, v5, v171 row_shr:1 row_mask:0xf bank_mask:0xf
	v_fmac_f32_dpp v138, v6, v172 row_shr:1 row_mask:0xf bank_mask:0xf
	v_fmac_f32_dpp v139, v7, v173 row_shr:1 row_mask:0xf bank_mask:0xf
	v_fmac_f32_dpp v132, v36, v154 row_shl:15 row_mask:0xf bank_mask:0xf
	v_fmac_f32_dpp v133, v37, v155 row_shl:15 row_mask:0xf bank_mask:0xf
	v_fmac_f32_dpp v134, v38, v156 row_shl:15 row_mask:0xf bank_mask:0xf
	v_fmac_f32_dpp v135, v39, v157 row_shl:15 row_mask:0xf bank_mask:0xf
	v_fmac_f32_dpp v136, v16, v170 row_shl:15 row_mask:0xf bank_mask:0xf
	v_fmac_f32_dpp v137, v17, v171 row_shl:15 row_mask:0xf bank_mask:0xf
	v_fmac_f32_dpp v138, v18, v172 row_shl:15 row_mask:0xf bank_mask:0xf
	v_fmac_f32_dpp v139, v19, v173 row_shl:15 row_mask:0xf bank_mask:0xf
	v_fmac_f32_dpp v132, v20, v150 row_shr:2 row_mask:0xf bank_mask:0xf
	v_fmac_f32_dpp v133, v21, v151 row_shr:2 row_mask:0xf bank_mask:0xf
	v_fmac_f32_dpp v134, v22, v152 row_shr:2 row_mask:0xf bank_mask:0xf
; __device__ __forceinline__ unsigned pk2(float lo, float hi) { unsigned r; asm("v_cvt_pk_bf16_f32 %0, %1, %2" : "=v"(r) : "v"(lo), "v"(hi)); return r; }
; __device__ __forceinline__ float gelu_tanh(float x) { const float y = 1.5957691216f * (x + 0.044715f * x * x * x); return x * __builtin_amdgcn_rcpf(1.0f + __expf(-y)); }
;     __device__ __forceinline__ void operator()(const f32x4 (&acc)[2][2][4][2], const Unit& u, int wr, int wc, int fr, int fq) const {
;     ...
;                 for (int m = 0; m < 4; ++m) { const int row = row0 + ai * HALF + m * 16;
;                     const f32x4 g0 = acc[ai][0][m][n], v0 = acc[ai][1][m][n];
;                     f32x4 gp = (f32x4){0.f, 0.f, 0.f, 0.f}, vp = gp;
;                     if (m > 0) { gp = acc[ai][0][m > 0 ? m - 1 : 0][n]; vp = acc[ai][1][m > 0 ? m - 1 : 0][n]; }
;                     f32x4 f;
; #pragma unroll
;                     for (int j = 0; j < 4; ++j) {
;                         const float g1 = dpp_shr1(dpp_ror1(gp[j]), g0[j]), g2 = dpp_shr2(dpp_ror2(gp[j]), g0[j]);
;                         const float v1 = dpp_shr1(dpp_ror1(vp[j]), v0[j]), v2 = dpp_shr2(dpp_ror2(vp[j]), v0[j]);
;                         const float cg_ = bg[j] + g2 * wg0[j] + g1 * wg1[j] + g0[j] * wg2[j];
;                         const float cv_ = bv[j] + v2 * wv0[j] + v1 * wv1[j] + v0[j] * wv2[j];
;                         f[j] = gelu_tanh(cg_) * cv_; }
;                     u32x2 w; w.x = pk2(f[0], f[1]); w.y = pk2(f[2], f[3]);
;                     if (n == 0) res0[ai * 4 + m] = w;
;                     else if (m > 0 || fr >= 2) { u32x4 w4; w4.x = res0[ai * 4 + m].x; w4.y = res0[ai * 4 + m].y; w4.z = w.x; w4.w = w.y; *(u32x4*)(F + (size_t)row * DFF + j0) = w4; }
;                     if (n == 1 && ((m == 0 && fr < 2) || (m == 3 && fr >= 14))) { const int slot = m == 0 ? fr : fr - 12;
;                         const f32x4 ga = acc[ai][0][m][0], va = acc[ai][1][m][0];
;                         bf16_t* bp = UPB + ((size_t)(row >> 6) * 4 + slot) * (2 * DFF) + col0;
;                         u32x4 wg_, wv_; wg_.x = pk2(ga[0], ga[1]); wg_.y = pk2(ga[2], ga[3]); wg_.z = pk2(g0[0], g0[1]); wg_.w = pk2(g0[2], g0[3]);
;                         wv_.x = pk2(va[0], va[1]); wv_.y = pk2(va[2], va[3]); wv_.z = pk2(v0[0], v0[1]); wv_.w = pk2(v0[2], v0[3]);
;                         *(u32x4*)bp = wg_; *(u32x4*)(bp + HALF) = wv_; } }
	v_fmac_f32_dpp v135, v23, v153 row_shr:2 row_mask:0xf bank_mask:0xf
	v_fmac_f32_dpp v136, v4, v166 row_shr:2 row_mask:0xf bank_mask:0xf
	v_fmac_f32_dpp v137, v5, v167 row_shr:2 row_mask:0xf bank_mask:0xf
	v_fmac_f32_dpp v138, v6, v168 row_shr:2 row_mask:0xf bank_mask:0xf
	v_fmac_f32_dpp v139, v7, v169 row_shr:2 row_mask:0xf bank_mask:0xf
	v_fmac_f32_dpp v132, v36, v150 row_shl:14 row_mask:0xf bank_mask:0xf
	v_fmac_f32_dpp v133, v37, v151 row_shl:14 row_mask:0xf bank_mask:0xf
	v_fmac_f32_dpp v134, v38, v152 row_shl:14 row_mask:0xf bank_mask:0xf
	v_fmac_f32_dpp v135, v39, v153 row_shl:14 row_mask:0xf bank_mask:0xf
	v_fmac_f32_dpp v136, v16, v166 row_shl:14 row_mask:0xf bank_mask:0xf
	v_fmac_f32_dpp v137, v17, v167 row_shl:14 row_mask:0xf bank_mask:0xf
	v_fmac_f32_dpp v138, v18, v168 row_shl:14 row_mask:0xf bank_mask:0xf
	v_fmac_f32_dpp v139, v19, v169 row_shl:14 row_mask:0xf bank_mask:0xf
	v_pk_mul_f32 v[140:141], v[132:133], v[132:133]
	v_pk_mul_f32 v[142:143], v[134:135], v[134:135]
	v_pk_fma_f32 v[140:141], v[140:141], s[98:99], v[244:245]
	v_pk_fma_f32 v[142:143], v[142:143], s[98:99], v[244:245]
	v_pk_mul_f32 v[140:141], v[132:133], v[140:141]
	v_pk_mul_f32 v[142:143], v[134:135], v[142:143]
	v_exp_f32_e32 v140, v140
	v_exp_f32_e32 v141, v141
	v_exp_f32_e32 v142, v142
	v_exp_f32_e32 v143, v143
	v_pk_add_f32 v[140:141], v[140:141], s[100:101]
	v_pk_add_f32 v[142:143], v[142:143], s[100:101]
	v_rcp_f32_e32 v140, v140
	v_rcp_f32_e32 v141, v141
	v_rcp_f32_e32 v142, v142
	v_rcp_f32_e32 v143, v143
	v_pk_mul_f32 v[140:141], v[132:133], v[140:141]
	v_pk_mul_f32 v[142:143], v[134:135], v[142:143]
	v_pk_mul_f32 v[140:141], v[140:141], v[136:137]
	v_pk_mul_f32 v[142:143], v[142:143], v[138:139]
	v_cvt_pk_bf16_f32 v250, v140, v141
	v_cvt_pk_bf16_f32 v251, v142, v143
	v_pk_fma_f32 v[132:133], v[12:13], v[190:191], v[178:179]
	v_pk_fma_f32 v[136:137], v[0:1], v[206:207], v[194:195]
	v_pk_fma_f32 v[134:135], v[14:15], v[192:193], v[180:181]
	v_pk_fma_f32 v[138:139], v[2:3], v[208:209], v[196:197]
	v_fmac_f32_dpp v132, v12, v186 row_shr:1 row_mask:0xf bank_mask:0xf
	v_fmac_f32_dpp v133, v13, v187 row_shr:1 row_mask:0xf bank_mask:0xf
	v_fmac_f32_dpp v134, v14, v188 row_shr:1 row_mask:0xf bank_mask:0xf
	v_fmac_f32_dpp v135, v15, v189 row_shr:1 row_mask:0xf bank_mask:0xf
	v_fmac_f32_dpp v136, v0, v202 row_shr:1 row_mask:0xf bank_mask:0xf
	v_fmac_f32_dpp v137, v1, v203 row_shr:1 row_mask:0xf bank_mask:0xf
	v_fmac_f32_dpp v138, v2, v204 row_shr:1 row_mask:0xf bank_mask:0xf
	v_fmac_f32_dpp v139, v3, v205 row_shr:1 row_mask:0xf bank_mask:0xf
	v_fmac_f32_dpp v132, v28, v186 row_shl:15 row_mask:0xf bank_mask:0xf
	v_fmac_f32_dpp v133, v29, v187 row_shl:15 row_mask:0xf bank_mask:0xf
	v_fmac_f32_dpp v134, v30, v188 row_shl:15 row_mask:0xf bank_mask:0xf
	v_fmac_f32_dpp v135, v31, v189 row_shl:15 row_mask:0xf bank_mask:0xf
	v_fmac_f32_dpp v136, v8, v202 row_shl:15 row_mask:0xf bank_mask:0xf
	v_fmac_f32_dpp v137, v9, v203 row_shl:15 row_mask:0xf bank_mask:0xf
	v_fmac_f32_dpp v138, v10, v204 row_shl:15 row_mask:0xf bank_mask:0xf
	v_fmac_f32_dpp v139, v11, v205 row_shl:15 row_mask:0xf bank_mask:0xf
	v_fmac_f32_dpp v132, v12, v182 row_shr:2 row_mask:0xf bank_mask:0xf
	v_fmac_f32_dpp v133, v13, v183 row_shr:2 row_mask:0xf bank_mask:0xf
	v_fmac_f32_dpp v134, v14, v184 row_shr:2 row_mask:0xf bank_mask:0xf
	v_fmac_f32_dpp v135, v15, v185 row_shr:2 row_mask:0xf bank_mask:0xf
	v_fmac_f32_dpp v136, v0, v198 row_shr:2 row_mask:0xf bank_mask:0xf
	v_fmac_f32_dpp v137, v1, v199 row_shr:2 row_mask:0xf bank_mask:0xf
	v_fmac_f32_dpp v138, v2, v200 row_shr:2 row_mask:0xf bank_mask:0xf
	v_fmac_f32_dpp v139, v3, v201 row_shr:2 row_mask:0xf bank_mask:0xf
	v_fmac_f32_dpp v132, v28, v182 row_shl:14 row_mask:0xf bank_mask:0xf
	v_fmac_f32_dpp v133, v29, v183 row_shl:14 row_mask:0xf bank_mask:0xf
	v_fmac_f32_dpp v134, v30, v184 row_shl:14 row_mask:0xf bank_mask:0xf
	v_fmac_f32_dpp v135, v31, v185 row_shl:14 row_mask:0xf bank_mask:0xf
	v_fmac_f32_dpp v136, v8, v198 row_shl:14 row_mask:0xf bank_mask:0xf
	v_fmac_f32_dpp v137, v9, v199 row_shl:14 row_mask:0xf bank_mask:0xf
	v_fmac_f32_dpp v138, v10, v200 row_shl:14 row_mask:0xf bank_mask:0xf
	v_fmac_f32_dpp v139, v11, v201 row_shl:14 row_mask:0xf bank_mask:0xf
	v_pk_mul_f32 v[140:141], v[132:133], v[132:133]
	v_pk_mul_f32 v[142:143], v[134:135], v[134:135]
	v_pk_fma_f32 v[140:141], v[140:141], s[98:99], v[244:245]
	v_pk_fma_f32 v[142:143], v[142:143], s[98:99], v[244:245]
	v_pk_mul_f32 v[140:141], v[132:133], v[140:141]
	v_pk_mul_f32 v[142:143], v[134:135], v[142:143]
	v_exp_f32_e32 v140, v140
	v_exp_f32_e32 v141, v141
	v_exp_f32_e32 v142, v142
	v_exp_f32_e32 v143, v143
	v_pk_add_f32 v[140:141], v[140:141], s[100:101]
	v_pk_add_f32 v[142:143], v[142:143], s[100:101]
	v_rcp_f32_e32 v140, v140
	v_rcp_f32_e32 v141, v141
	v_rcp_f32_e32 v142, v142
	v_rcp_f32_e32 v143, v143
	v_pk_mul_f32 v[140:141], v[132:133], v[140:141]
	v_pk_mul_f32 v[142:143], v[134:135], v[142:143]
	v_pk_mul_f32 v[140:141], v[140:141], v[136:137]
	v_pk_mul_f32 v[142:143], v[142:143], v[138:139]
	v_cvt_pk_bf16_f32 v252, v140, v141
	v_cvt_pk_bf16_f32 v253, v142, v143
	v_add_u32_e32 v144, 0xb0, v248
	v_mad_u64_u32 v[144:145], vcc, v144, s4, v[242:243]
	global_store_dwordx4 v[144:145], v[250:253], off nt
	s_mov_b64 s[0:1], 0
	s_and_saveexec_b64 s[42:43], s[12:13]
	s_xor_b64 s[52:53], exec, s[42:43]
	s_cbranch_execz .LBB0_1214
	v_add_u32_e32 v144, s73, v234
	v_mov_b64_e32 v[132:133], s[80:81]
	v_mad_u64_u32 v[132:133], vcc, v144, s83, v[132:133]
	v_lshl_add_u64 v[132:133], v[240:241], 1, v[132:133]
	s_mov_b64 s[72:73], exec
	v_cvt_pk_bf16_f32 v134, v20, v21
	v_cvt_pk_bf16_f32 v135, v22, v23
	v_cvt_pk_bf16_f32 v136, v12, v13
	v_cvt_pk_bf16_f32 v137, v14, v15
	v_cvt_pk_bf16_f32 v128, v4, v5
	v_cvt_pk_bf16_f32 v129, v6, v7
	v_cvt_pk_bf16_f32 v130, v0, v1
	v_cvt_pk_bf16_f32 v131, v2, v3
	global_store_dwordx4 v[132:133], v[134:137], off
